# non-temporal hints also on the last-use loads of the LayerNorm and merge phases (every buffer read exactly once there)
# speedup vs baseline: 1.0140x; 1.0034x over previous
; __device__ __forceinline__ float bflo(unsigned u) { return __uint_as_float(u << 16); }
; __device__ __forceinline__ float bfhi(unsigned u) { return __uint_as_float(u & 0xffff0000u); }
; __device__ void ln_phase2(const bf16_t* __restrict__ mix, const float* __restrict__ Rf, const bf16_t* __restrict__ Rb, const float* __restrict__ gam, const float* __restrict__ bet, bf16_t* ob, float* of) {
;     ...
;     for (int row = blockIdx.x * 8 + wid; row < T_TOK; row += gridDim.x * 8) {
;         const size_t ro = (size_t)row * DM + lane * 8;
;         float v[32]; float s = 0.f;
; #pragma unroll
;         for (int j = 0; j < 4; ++j) {
;             const u32x4 m = *(const u32x4*)(mix + ro + 512 * j);
;             float r[8];
;             if (Rf) { const f32x4 a = *(const f32x4*)(Rf + ro + 512 * j), b = *(const f32x4*)(Rf + ro + 512 * j + 4);
;                 r[0] = a[0]; r[1] = a[1]; r[2] = a[2]; r[3] = a[3]; r[4] = b[0]; r[5] = b[1]; r[6] = b[2]; r[7] = b[3]; }
;             else { const u32x4 rb = *(const u32x4*)(Rb + ro + 512 * j);
;                 r[0] = bflo(rb.x); r[1] = bfhi(rb.x); r[2] = bflo(rb.y); r[3] = bfhi(rb.y); r[4] = bflo(rb.z); r[5] = bfhi(rb.z); r[6] = bflo(rb.w); r[7] = bfhi(rb.w); }
;             v[8 * j + 0] = DN_ALPHA * r[0] + bflo(m.x); v[8 * j + 1] = DN_ALPHA * r[1] + bfhi(m.x); v[8 * j + 2] = DN_ALPHA * r[2] + bflo(m.y); v[8 * j + 3] = DN_ALPHA * r[3] + bfhi(m.y);
;             v[8 * j + 4] = DN_ALPHA * r[4] + bflo(m.z); v[8 * j + 5] = DN_ALPHA * r[5] + bfhi(m.z); v[8 * j + 6] = DN_ALPHA * r[6] + bflo(m.w); v[8 * j + 7] = DN_ALPHA * r[7] + bfhi(m.w);
; #pragma unroll
;             for (int e = 0; e < 8; ++e) s += v[8 * j + e];
;         }
; #pragma unroll
;         for (int o = 32; o; o >>= 1) s += __shfl_xor(s, o);
.LBB0_31:
	v_ashrrev_i32_e32 v1, 31, v0
	v_lshlrev_b64 v[88:89], 11, v[0:1]
	v_or_b32_e32 v88, v88, v84
	v_lshlrev_b64 v[68:69], 1, v[88:89]
	v_lshl_add_u64 v[70:71], s[68:69], 0, v[68:69]
	v_lshl_add_u64 v[72:73], s[92:93], 0, v[68:69]
	global_load_dwordx4 v[94:97], v[70:71], off nt
	global_load_dwordx4 v[98:101], v[72:73], off nt
	global_load_dwordx4 v[110:113], v[70:71], off offset:1024 nt
	global_load_dwordx4 v[114:117], v[72:73], off offset:1024 nt
	global_load_dwordx4 v[76:79], v[70:71], off offset:2048 nt
	global_load_dwordx4 v[80:83], v[72:73], off offset:2048 nt
	s_nop 0
	global_load_dwordx4 v[68:71], v[70:71], off offset:3072 nt
	s_nop 0
	global_load_dwordx4 v[72:75], v[72:73], off offset:3072 nt
	v_add_u32_e32 v0, s10, v0
	s_waitcnt vmcnt(0)
	v_lshlrev_b32_e32 v92, 16, v97
	v_and_b32_e32 v93, 0xffff0000, v97
	v_and_b32_e32 v97, 0xffff0000, v94
	s_waitcnt vmcnt(5)
	v_lshlrev_b32_e32 v102, 16, v110
	v_and_b32_e32 v103, 0xffff0000, v110
	v_lshlrev_b32_e32 v104, 16, v111
	s_waitcnt vmcnt(1)
	v_and_b32_e32 v90, 0xffff0000, v70
	s_waitcnt vmcnt(0)
	v_and_b32_e32 v86, 0xffff0000, v74
	v_lshlrev_b32_e32 v87, 16, v74
	v_lshlrev_b32_e32 v91, 16, v70
	v_and_b32_e32 v74, 0xffff0000, v75
	v_lshlrev_b32_e32 v75, 16, v75
	v_and_b32_e32 v70, 0xffff0000, v71
	v_lshlrev_b32_e32 v71, 16, v71
	v_pk_fma_f32 v[86:87], v[86:87], s[4:5], v[90:91] op_sel_hi:[1,0,1]
	v_pk_fma_f32 v[74:75], v[74:75], s[4:5], v[70:71] op_sel_hi:[1,0,1]
	v_lshl_add_u64 v[70:71], v[88:89], 2, s[90:91]
	v_lshlrev_b32_e32 v88, 16, v100
	v_and_b32_e32 v89, 0xffff0000, v100
	v_lshlrev_b32_e32 v90, 16, v96
	v_and_b32_e32 v91, 0xffff0000, v96
	v_pk_fma_f32 v[88:89], v[88:89], s[4:5], v[90:91] op_sel_hi:[1,0,1]
	v_lshlrev_b32_e32 v90, 16, v101
	v_and_b32_e32 v91, 0xffff0000, v101
	v_pk_fma_f32 v[90:91], v[90:91], s[4:5], v[92:93] op_sel_hi:[1,0,1]
	v_lshlrev_b32_e32 v92, 16, v98
	v_and_b32_e32 v93, 0xffff0000, v98
	v_lshlrev_b32_e32 v96, 16, v94
	v_pk_fma_f32 v[92:93], v[92:93], s[4:5], v[96:97] op_sel_hi:[1,0,1]
	v_lshlrev_b32_e32 v96, 16, v99
	v_add_f32_e32 v1, 0, v92
	v_and_b32_e32 v97, 0xffff0000, v99
	v_lshlrev_b32_e32 v94, 16, v95
	v_and_b32_e32 v95, 0xffff0000, v95
	v_add_f32_e32 v1, v93, v1
	v_pk_fma_f32 v[94:95], v[96:97], s[4:5], v[94:95] op_sel_hi:[1,0,1]
	v_lshlrev_b32_e32 v96, 16, v116
	v_add_f32_e32 v1, v94, v1
	v_add_f32_e32 v1, v95, v1
	v_add_f32_e32 v1, v88, v1
	v_and_b32_e32 v97, 0xffff0000, v116
	v_lshlrev_b32_e32 v98, 16, v112
	v_and_b32_e32 v99, 0xffff0000, v112
	v_add_f32_e32 v1, v89, v1
	v_pk_fma_f32 v[96:97], v[96:97], s[4:5], v[98:99] op_sel_hi:[1,0,1]
	v_lshlrev_b32_e32 v98, 16, v117
	v_and_b32_e32 v99, 0xffff0000, v117
	v_lshlrev_b32_e32 v100, 16, v113
	v_and_b32_e32 v101, 0xffff0000, v113
	v_add_f32_e32 v1, v90, v1
	v_pk_fma_f32 v[98:99], v[98:99], s[4:5], v[100:101] op_sel_hi:[1,0,1]
	v_lshlrev_b32_e32 v100, 16, v114
	v_and_b32_e32 v101, 0xffff0000, v114
	v_add_f32_e32 v1, v91, v1
	v_pk_fma_f32 v[102:103], v[100:101], s[4:5], v[102:103] op_sel_hi:[1,0,1]
	v_lshlrev_b32_e32 v100, 16, v115
	v_add_f32_e32 v1, v102, v1
	v_and_b32_e32 v101, 0xffff0000, v115
	v_and_b32_e32 v105, 0xffff0000, v111
	v_add_f32_e32 v1, v103, v1
	v_pk_fma_f32 v[104:105], v[100:101], s[4:5], v[104:105] op_sel_hi:[1,0,1]
	v_lshlrev_b32_e32 v100, 16, v82
	v_add_f32_e32 v1, v104, v1
	v_add_f32_e32 v1, v105, v1
	v_add_f32_e32 v1, v96, v1
	v_add_f32_e32 v1, v97, v1
	v_and_b32_e32 v101, 0xffff0000, v82
	v_lshlrev_b32_e32 v110, 16, v78
	v_and_b32_e32 v111, 0xffff0000, v78
	v_lshlrev_b32_e32 v82, 16, v83
	v_and_b32_e32 v83, 0xffff0000, v83
	v_lshlrev_b32_e32 v78, 16, v79
	v_and_b32_e32 v79, 0xffff0000, v79
	v_add_f32_e32 v1, v98, v1
	v_pk_fma_f32 v[100:101], v[100:101], s[4:5], v[110:111] op_sel_hi:[1,0,1]
	v_pk_fma_f32 v[78:79], v[82:83], s[4:5], v[78:79] op_sel_hi:[1,0,1]
	v_lshlrev_b32_e32 v82, 16, v80
	v_and_b32_e32 v83, 0xffff0000, v80
	v_lshlrev_b32_e32 v110, 16, v76
	v_and_b32_e32 v111, 0xffff0000, v76
	v_add_f32_e32 v1, v99, v1
	v_pk_fma_f32 v[82:83], v[82:83], s[4:5], v[110:111] op_sel_hi:[1,0,1]
	v_lshlrev_b32_e32 v80, 16, v81
	v_add_f32_e32 v1, v82, v1
	v_and_b32_e32 v81, 0xffff0000, v81
	v_lshlrev_b32_e32 v76, 16, v77
	v_and_b32_e32 v77, 0xffff0000, v77
	v_add_f32_e32 v1, v83, v1
	v_pk_fma_f32 v[76:77], v[80:81], s[4:5], v[76:77] op_sel_hi:[1,0,1]
	v_lshlrev_b32_e32 v80, 16, v72
	v_add_f32_e32 v1, v76, v1
	v_add_f32_e32 v1, v77, v1
	v_add_f32_e32 v1, v100, v1
	v_add_f32_e32 v1, v101, v1
	v_add_f32_e32 v1, v78, v1
	v_and_b32_e32 v81, 0xffff0000, v72
	v_lshlrev_b32_e32 v110, 16, v68
	v_and_b32_e32 v111, 0xffff0000, v68
	v_add_f32_e32 v1, v79, v1
	v_pk_fma_f32 v[80:81], v[80:81], s[4:5], v[110:111] op_sel_hi:[1,0,1]
	v_lshlrev_b32_e32 v72, 16, v73
	v_add_f32_e32 v1, v80, v1
	v_and_b32_e32 v73, 0xffff0000, v73
	v_lshlrev_b32_e32 v68, 16, v69
	v_and_b32_e32 v69, 0xffff0000, v69
	v_add_f32_e32 v1, v81, v1
	v_pk_fma_f32 v[68:69], v[72:73], s[4:5], v[68:69] op_sel_hi:[1,0,1]
	s_nop 0
	v_add_f32_e32 v1, v68, v1
	v_add_f32_e32 v1, v69, v1
	v_add_f32_e32 v1, v87, v1
	v_add_f32_e32 v1, v86, v1
	v_add_f32_e32 v1, v75, v1
	v_add_f32_e32 v1, v74, v1
	v_mov_b32_e32 v72, v1
	s_nop 1
	v_permlane32_swap_b32 v72, v1
	v_add_f32_e32 v1, v1, v72
	v_mov_b32_e32 v72, v1
	s_nop 1
	v_permlane16_swap_b32 v72, v1
	v_add_f32_e32 v1, v1, v72
	s_nop 1
	v_add_f32_dpp v1, v1, v1 quad_perm:[1,0,3,2] row_mask:0xf bank_mask:0xf
	s_nop 1
	v_add_f32_dpp v1, v1, v1 quad_perm:[2,3,0,1] row_mask:0xf bank_mask:0xf
	s_nop 1
	v_add_f32_dpp v1, v1, v1 row_half_mirror row_mask:0xf bank_mask:0xf
	s_nop 1
	v_add_f32_dpp v1, v1, v1 row_mirror row_mask:0xf bank_mask:0xf
	v_mul_f32_e32 v72, 0x3a000000, v1
; __device__ __forceinline__ unsigned cvt_pk_bf16(float lo, float hi) { const f32x2v v = {lo, hi}; const b16x2v r = __builtin_convertvector(v, b16x2v); return __builtin_bit_cast(unsigned, r); }
; __device__ void ln_phase2(const bf16_t* __restrict__ mix, const float* __restrict__ Rf, const bf16_t* __restrict__ Rb, const float* __restrict__ gam, const float* __restrict__ bet, bf16_t* ob, float* of) {
;     ...
;         float q = 0.f;
; #pragma unroll
;         for (int e = 0; e < 32; ++e) { const float dlt = v[e] - mean; q += dlt * dlt; }
; #pragma unroll
;         for (int o = 32; o; o >>= 1) q += __shfl_xor(q, o);
;         const float rstd = rsqrtf(q * (1.0f / 2048.0f) + 1e-5f);
; #pragma unroll
;         for (int j = 0; j < 4; ++j) {
;             const f32x4 g0 = *(const f32x4*)(gam + lane * 8 + 512 * j), g1 = *(const f32x4*)(gam + lane * 8 + 512 * j + 4);
;             const f32x4 b0 = *(const f32x4*)(bet + lane * 8 + 512 * j), b1 = *(const f32x4*)(bet + lane * 8 + 512 * j + 4);
;             f32x4 y0, y1;
; #pragma unroll
;             for (int e = 0; e < 4; ++e) { y0[e] = (v[8 * j + e] - mean) * rstd * g0[e] + b0[e]; y1[e] = (v[8 * j + 4 + e] - mean) * rstd * g1[e] + b1[e]; }
;             if (ob) { u32x4 w; w.x = cvt_pk_bf16(y0[0], y0[1]); w.y = cvt_pk_bf16(y0[2], y0[3]); w.z = cvt_pk_bf16(y1[0], y1[1]); w.w = cvt_pk_bf16(y1[2], y1[3]); *(u32x4*)(ob + ro + 512 * j) = w; }
;             else { *(f32x4*)(of + ro + 512 * j) = y0; *(f32x4*)(of + ro + 512 * j + 4) = y1; }
;         }
	v_pk_add_f32 v[92:93], v[92:93], v[72:73] op_sel_hi:[1,0] neg_lo:[0,1] neg_hi:[0,1]
	v_pk_add_f32 v[94:95], v[94:95], v[72:73] op_sel_hi:[1,0] neg_lo:[0,1] neg_hi:[0,1]
	v_pk_mul_f32 v[110:111], v[92:93], v[92:93]
	v_pk_mul_f32 v[112:113], v[94:95], v[94:95]
	v_add_f32_e32 v1, v110, v111
	v_pk_add_f32 v[88:89], v[88:89], v[72:73] op_sel_hi:[1,0] neg_lo:[0,1] neg_hi:[0,1]
	v_add_f32_e32 v1, v112, v1
	v_pk_mul_f32 v[114:115], v[88:89], v[88:89]
	v_add_f32_e32 v1, v113, v1
	v_pk_add_f32 v[90:91], v[90:91], v[72:73] op_sel_hi:[1,0] neg_lo:[0,1] neg_hi:[0,1]
	v_add_f32_e32 v1, v114, v1
	v_pk_mul_f32 v[116:117], v[90:91], v[90:91]
	v_add_f32_e32 v1, v115, v1
	v_pk_add_f32 v[102:103], v[102:103], v[72:73] op_sel_hi:[1,0] neg_lo:[0,1] neg_hi:[0,1]
	v_add_f32_e32 v1, v116, v1
	v_pk_mul_f32 v[118:119], v[102:103], v[102:103]
	v_add_f32_e32 v1, v117, v1
	v_pk_add_f32 v[104:105], v[104:105], v[72:73] op_sel_hi:[1,0] neg_lo:[0,1] neg_hi:[0,1]
	v_add_f32_e32 v1, v118, v1
	v_pk_mul_f32 v[120:121], v[104:105], v[104:105]
	v_add_f32_e32 v1, v119, v1
	v_pk_add_f32 v[96:97], v[96:97], v[72:73] op_sel_hi:[1,0] neg_lo:[0,1] neg_hi:[0,1]
	v_add_f32_e32 v1, v120, v1
	v_pk_mul_f32 v[122:123], v[96:97], v[96:97]
	v_add_f32_e32 v1, v121, v1
	v_pk_add_f32 v[98:99], v[98:99], v[72:73] op_sel_hi:[1,0] neg_lo:[0,1] neg_hi:[0,1]
	v_add_f32_e32 v1, v122, v1
	v_pk_mul_f32 v[124:125], v[98:99], v[98:99]
	v_add_f32_e32 v1, v123, v1
	v_pk_add_f32 v[82:83], v[82:83], v[72:73] op_sel_hi:[1,0] neg_lo:[0,1] neg_hi:[0,1]
	v_add_f32_e32 v1, v124, v1
	v_pk_mul_f32 v[126:127], v[82:83], v[82:83]
	v_add_f32_e32 v1, v125, v1
	v_pk_add_f32 v[128:129], v[76:77], v[72:73] op_sel_hi:[1,0] neg_lo:[0,1] neg_hi:[0,1]
	v_add_f32_e32 v1, v126, v1
	v_pk_mul_f32 v[76:77], v[128:129], v[128:129]
	v_add_f32_e32 v1, v127, v1
	v_pk_add_f32 v[100:101], v[100:101], v[72:73] op_sel_hi:[1,0] neg_lo:[0,1] neg_hi:[0,1]
	v_add_f32_e32 v1, v76, v1
	v_pk_mul_f32 v[130:131], v[100:101], v[100:101]
	v_add_f32_e32 v1, v77, v1
	v_pk_add_f32 v[132:133], v[78:79], v[72:73] op_sel_hi:[1,0] neg_lo:[0,1] neg_hi:[0,1]
	v_add_f32_e32 v1, v130, v1
	v_pk_mul_f32 v[78:79], v[132:133], v[132:133]
	v_add_f32_e32 v1, v131, v1
	v_pk_add_f32 v[80:81], v[80:81], v[72:73] op_sel_hi:[1,0] neg_lo:[0,1] neg_hi:[0,1]
	v_add_f32_e32 v1, v78, v1
	v_pk_mul_f32 v[134:135], v[80:81], v[80:81]
	v_add_f32_e32 v1, v79, v1
	v_pk_add_f32 v[136:137], v[68:69], v[72:73] op_sel_hi:[1,0] neg_lo:[0,1] neg_hi:[0,1]
	v_add_f32_e32 v1, v134, v1
	v_pk_mul_f32 v[68:69], v[136:137], v[136:137]
	v_add_f32_e32 v1, v135, v1
	v_pk_add_f32 v[86:87], v[86:87], v[72:73] op_sel_hi:[1,0] neg_lo:[0,1] neg_hi:[0,1]
	v_add_f32_e32 v1, v68, v1
	v_pk_mul_f32 v[138:139], v[86:87], v[86:87]
	v_add_f32_e32 v1, v69, v1
	v_pk_add_f32 v[140:141], v[74:75], v[72:73] op_sel_hi:[1,0] neg_lo:[0,1] neg_hi:[0,1]
	v_add_f32_e32 v1, v139, v1
	v_pk_mul_f32 v[72:73], v[140:141], v[140:141]
	v_add_f32_e32 v1, v138, v1
	v_add_f32_e32 v1, v73, v1
	v_add_f32_e32 v1, v72, v1
	v_mov_b32_e32 v68, v1
	s_nop 1
	v_permlane32_swap_b32 v68, v1
	v_add_f32_e32 v1, v1, v68
	v_mov_b32_e32 v68, v1
	s_nop 1
	v_permlane16_swap_b32 v68, v1
	v_add_f32_e32 v1, v1, v68
	s_nop 1
	v_add_f32_dpp v1, v1, v1 quad_perm:[1,0,3,2] row_mask:0xf bank_mask:0xf
	s_nop 1
	v_add_f32_dpp v1, v1, v1 quad_perm:[2,3,0,1] row_mask:0xf bank_mask:0xf
	s_nop 1
	v_add_f32_dpp v1, v1, v1 row_half_mirror row_mask:0xf bank_mask:0xf
	s_nop 1
	v_add_f32_dpp v1, v1, v1 row_mirror row_mask:0xf bank_mask:0xf
	v_fmamk_f32 v1, v1, 0x3a000000, v213
	v_cmp_gt_f32_e32 vcc, s12, v1
	v_mul_f32_e32 v68, 0x4b800000, v1
	s_nop 0
	v_cndmask_b32_e32 v1, v1, v68, vcc
	v_rsq_f32_e32 v1, v1
	s_nop 0
	v_mul_f32_e32 v68, 0x45800000, v1
	v_cndmask_b32_e32 v110, v1, v68, vcc
	v_pk_mul_f32 v[68:69], v[92:93], v[110:111] op_sel_hi:[1,0]
	v_pk_mul_f32 v[72:73], v[94:95], v[110:111] op_sel_hi:[1,0]
	v_pk_mul_f32 v[76:77], v[90:91], v[110:111] op_sel_hi:[1,0]
	v_pk_fma_f32 v[74:75], v[10:11], v[72:73], v[18:19]
	v_pk_fma_f32 v[72:73], v[8:9], v[68:69], v[16:17]
	v_pk_mul_f32 v[68:69], v[88:89], v[110:111] op_sel_hi:[1,0]
	v_pk_fma_f32 v[78:79], v[6:7], v[76:77], v[14:15]
	v_pk_fma_f32 v[76:77], v[4:5], v[68:69], v[12:13]
	global_store_dwordx4 v[70:71], v[72:75], off nt
	global_store_dwordx4 v[70:71], v[76:79], off offset:16 nt
	v_pk_mul_f32 v[68:69], v[102:103], v[110:111] op_sel_hi:[1,0]
	v_pk_mul_f32 v[72:73], v[104:105], v[110:111] op_sel_hi:[1,0]
	v_pk_mul_f32 v[76:77], v[98:99], v[110:111] op_sel_hi:[1,0]
	v_pk_fma_f32 v[74:75], v[26:27], v[72:73], v[34:35]
	v_pk_fma_f32 v[72:73], v[24:25], v[68:69], v[32:33]
	v_pk_mul_f32 v[68:69], v[96:97], v[110:111] op_sel_hi:[1,0]
	v_pk_fma_f32 v[78:79], v[22:23], v[76:77], v[30:31]
	v_pk_fma_f32 v[76:77], v[20:21], v[68:69], v[28:29]
	global_store_dwordx4 v[70:71], v[72:75], off offset:2048 nt
	global_store_dwordx4 v[70:71], v[76:79], off offset:2064 nt
	v_pk_mul_f32 v[68:69], v[82:83], v[110:111] op_sel_hi:[1,0]
	v_pk_mul_f32 v[72:73], v[128:129], v[110:111] op_sel_hi:[1,0]
	v_add_co_u32_e32 v82, vcc, s11, v70
	v_pk_fma_f32 v[74:75], v[38:39], v[72:73], v[46:47]
	v_pk_fma_f32 v[72:73], v[36:37], v[68:69], v[44:45]
	v_pk_mul_f32 v[68:69], v[100:101], v[110:111] op_sel_hi:[1,0]
	v_pk_mul_f32 v[76:77], v[132:133], v[110:111] op_sel_hi:[1,0]
	v_addc_co_u32_e32 v83, vcc, 0, v71, vcc
	v_pk_fma_f32 v[78:79], v[42:43], v[76:77], v[50:51]
	v_pk_fma_f32 v[76:77], v[40:41], v[68:69], v[48:49]
	global_store_dwordx4 v[82:83], v[72:75], off nt
	global_store_dwordx4 v[82:83], v[76:79], off offset:16 nt
	v_cmp_lt_i32_e32 vcc, s13, v0
	v_pk_mul_f32 v[72:73], v[80:81], v[110:111] op_sel_hi:[1,0]
	v_pk_mul_f32 v[74:75], v[136:137], v[110:111] op_sel_hi:[1,0]
	v_pk_mul_f32 v[68:69], v[86:87], v[110:111] op_sel_hi:[1,0]
	v_pk_mul_f32 v[70:71], v[140:141], v[110:111] op_sel_hi:[1,0]
	v_pk_fma_f32 v[74:75], v[54:55], v[74:75], v[62:63]
	v_pk_fma_f32 v[72:73], v[52:53], v[72:73], v[60:61]
	s_or_b64 s[2:3], vcc, s[2:3]
	v_pk_fma_f32 v[68:69], v[56:57], v[68:69], v[64:65] op_sel:[0,1,0] op_sel_hi:[1,0,1]
	v_pk_fma_f32 v[70:71], v[58:59], v[70:71], v[66:67] op_sel:[0,1,0] op_sel_hi:[1,0,1]
	global_store_dwordx4 v[82:83], v[72:75], off offset:2048 nt
	global_store_dwordx4 v[82:83], v[68:71], off offset:2064 nt
	s_andn2_b64 exec, exec, s[2:3]
	s_cbranch_execnz .LBB0_31

; __device__ __forceinline__ float bflo(unsigned u) { return __uint_as_float(u << 16); }
; __device__ __forceinline__ float bfhi(unsigned u) { return __uint_as_float(u & 0xffff0000u); }
; __device__ void ln_phase2(const bf16_t* __restrict__ mix, const float* __restrict__ Rf, const bf16_t* __restrict__ Rb, const float* __restrict__ gam, const float* __restrict__ bet, bf16_t* ob, float* of) {
;     ...
;     for (int row = blockIdx.x * 8 + wid; row < T_TOK; row += gridDim.x * 8) {
;         const size_t ro = (size_t)row * DM + lane * 8;
;         float v[32]; float s = 0.f;
; #pragma unroll
;         for (int j = 0; j < 4; ++j) {
;             const u32x4 m = *(const u32x4*)(mix + ro + 512 * j);
;             float r[8];
;             if (Rf) { const f32x4 a = *(const f32x4*)(Rf + ro + 512 * j), b = *(const f32x4*)(Rf + ro + 512 * j + 4);
;                 r[0] = a[0]; r[1] = a[1]; r[2] = a[2]; r[3] = a[3]; r[4] = b[0]; r[5] = b[1]; r[6] = b[2]; r[7] = b[3]; }
;             else { const u32x4 rb = *(const u32x4*)(Rb + ro + 512 * j);
;                 r[0] = bflo(rb.x); r[1] = bfhi(rb.x); r[2] = bflo(rb.y); r[3] = bfhi(rb.y); r[4] = bflo(rb.z); r[5] = bfhi(rb.z); r[6] = bflo(rb.w); r[7] = bfhi(rb.w); }
;             v[8 * j + 0] = DN_ALPHA * r[0] + bflo(m.x); v[8 * j + 1] = DN_ALPHA * r[1] + bfhi(m.x); v[8 * j + 2] = DN_ALPHA * r[2] + bflo(m.y); v[8 * j + 3] = DN_ALPHA * r[3] + bfhi(m.y);
;             v[8 * j + 4] = DN_ALPHA * r[4] + bflo(m.z); v[8 * j + 5] = DN_ALPHA * r[5] + bfhi(m.z); v[8 * j + 6] = DN_ALPHA * r[6] + bflo(m.w); v[8 * j + 7] = DN_ALPHA * r[7] + bfhi(m.w);
; #pragma unroll
;             for (int e = 0; e < 8; ++e) s += v[8 * j + e];
;         }
; #pragma unroll
;         for (int o = 32; o; o >>= 1) s += __shfl_xor(s, o);
;         const float mean = s * (1.0f / 2048.0f);
.LBB0_57:
	v_ashrrev_i32_e32 v1, 31, v0
	v_lshlrev_b64 v[78:79], 11, v[0:1]
	v_or_b32_e32 v78, v78, v76
	v_readlane_b32 s0, v254, 11
	v_lshlrev_b64 v[80:81], 1, v[78:79]
	v_readlane_b32 s1, v254, 12
	v_lshl_add_u64 v[84:85], s[64:65], 0, v[80:81]
	v_readlane_b32 s10, v251, 12
	v_lshl_add_u64 v[82:83], s[0:1], 0, v[80:81]
	global_load_dwordx4 v[68:71], v[82:83], off nt
	global_load_dwordx4 v[72:75], v[84:85], off nt
	global_load_dwordx4 v[98:101], v[82:83], off offset:1024 nt
	global_load_dwordx4 v[104:107], v[84:85], off offset:1024 nt
	global_load_dwordx4 v[112:115], v[82:83], off offset:2048 nt
	global_load_dwordx4 v[116:119], v[84:85], off offset:2048 nt
	global_load_dwordx4 v[88:91], v[82:83], off offset:3072 nt
	global_load_dwordx4 v[92:95], v[84:85], off offset:3072 nt
	s_mov_b32 s0, 0x3f9837f0
	v_readlane_b32 s11, v251, 13
	v_lshl_add_u64 v[80:81], s[92:93], 0, v[80:81]
	s_waitcnt vmcnt(0)
	v_lshlrev_b32_e32 v96, 16, v114
	v_and_b32_e32 v97, 0xffff0000, v114
	s_waitcnt vmcnt(1)
	v_lshlrev_b32_e32 v84, 16, v91
	s_waitcnt vmcnt(0)
	v_lshlrev_b32_e32 v82, 16, v95
	v_and_b32_e32 v83, 0xffff0000, v95
	v_and_b32_e32 v85, 0xffff0000, v91
	v_pk_fma_f32 v[82:83], v[82:83], s[0:1], v[84:85] op_sel_hi:[1,0,1]
	v_lshlrev_b32_e32 v84, 16, v93
	v_and_b32_e32 v85, 0xffff0000, v93
	v_lshlrev_b32_e32 v86, 16, v89
	v_and_b32_e32 v87, 0xffff0000, v89
	v_pk_fma_f32 v[84:85], v[84:85], s[0:1], v[86:87] op_sel_hi:[1,0,1]
	v_lshlrev_b32_e32 v86, 16, v94
	v_and_b32_e32 v87, 0xffff0000, v94
	v_lshlrev_b32_e32 v94, 16, v90
	v_and_b32_e32 v95, 0xffff0000, v90
	v_lshlrev_b32_e32 v90, 16, v92
	v_and_b32_e32 v91, 0xffff0000, v92
	v_lshlrev_b32_e32 v92, 16, v88
	v_and_b32_e32 v93, 0xffff0000, v88
	v_pk_fma_f32 v[88:89], v[90:91], s[0:1], v[92:93] op_sel_hi:[1,0,1]
	v_lshlrev_b32_e32 v90, 16, v119
	v_and_b32_e32 v91, 0xffff0000, v119
	v_lshlrev_b32_e32 v92, 16, v115
	v_and_b32_e32 v93, 0xffff0000, v115
	v_pk_fma_f32 v[86:87], v[86:87], s[0:1], v[94:95] op_sel_hi:[1,0,1]
	v_pk_fma_f32 v[90:91], v[90:91], s[0:1], v[92:93] op_sel_hi:[1,0,1]
	v_lshlrev_b32_e32 v92, 16, v117
	v_and_b32_e32 v93, 0xffff0000, v117
	v_lshlrev_b32_e32 v94, 16, v113
	v_and_b32_e32 v95, 0xffff0000, v113
	v_pk_fma_f32 v[94:95], v[92:93], s[0:1], v[94:95] op_sel_hi:[1,0,1]
	v_lshlrev_b32_e32 v92, 16, v118
	v_and_b32_e32 v93, 0xffff0000, v118
	v_pk_fma_f32 v[92:93], v[92:93], s[0:1], v[96:97] op_sel_hi:[1,0,1]
	v_lshlrev_b32_e32 v96, 16, v116
	v_and_b32_e32 v97, 0xffff0000, v116
	v_lshlrev_b32_e32 v102, 16, v112
	v_and_b32_e32 v103, 0xffff0000, v112
	v_pk_fma_f32 v[96:97], v[96:97], s[0:1], v[102:103] op_sel_hi:[1,0,1]
	v_lshlrev_b32_e32 v102, 16, v107
	v_and_b32_e32 v103, 0xffff0000, v107
	v_lshlrev_b32_e32 v112, 16, v101
	v_and_b32_e32 v113, 0xffff0000, v101
	v_pk_fma_f32 v[102:103], v[102:103], s[0:1], v[112:113] op_sel_hi:[1,0,1]
	v_lshlrev_b32_e32 v112, 16, v105
	v_and_b32_e32 v113, 0xffff0000, v105
	v_lshlrev_b32_e32 v114, 16, v99
	v_and_b32_e32 v115, 0xffff0000, v99
	v_pk_fma_f32 v[112:113], v[112:113], s[0:1], v[114:115] op_sel_hi:[1,0,1]
	v_lshlrev_b32_e32 v114, 16, v106
	v_and_b32_e32 v115, 0xffff0000, v106
	v_lshlrev_b32_e32 v106, 16, v100
	v_and_b32_e32 v107, 0xffff0000, v100
	v_pk_fma_f32 v[100:101], v[114:115], s[0:1], v[106:107] op_sel_hi:[1,0,1]
	v_lshlrev_b32_e32 v106, 16, v104
	v_and_b32_e32 v107, 0xffff0000, v104
	v_lshlrev_b32_e32 v104, 16, v98
	v_and_b32_e32 v105, 0xffff0000, v98
	v_pk_fma_f32 v[106:107], v[106:107], s[0:1], v[104:105] op_sel_hi:[1,0,1]
	v_lshlrev_b32_e32 v98, 16, v73
	v_and_b32_e32 v99, 0xffff0000, v73
	v_lshlrev_b32_e32 v104, 16, v69
	v_and_b32_e32 v105, 0xffff0000, v69
	v_pk_fma_f32 v[104:105], v[98:99], s[0:1], v[104:105] op_sel_hi:[1,0,1]
	v_lshlrev_b32_e32 v98, 16, v72
	v_and_b32_e32 v99, 0xffff0000, v72
	v_lshlrev_b32_e32 v72, 16, v68
	v_and_b32_e32 v73, 0xffff0000, v68
	v_pk_fma_f32 v[68:69], v[98:99], s[0:1], v[72:73] op_sel_hi:[1,0,1]
	v_lshlrev_b32_e32 v72, 16, v75
	v_add_f32_e32 v1, 0, v68
	v_add_f32_e32 v1, v69, v1
	v_and_b32_e32 v73, 0xffff0000, v75
	v_lshlrev_b32_e32 v98, 16, v71
	v_and_b32_e32 v99, 0xffff0000, v71
	v_add_f32_e32 v1, v104, v1
	v_pk_fma_f32 v[72:73], v[72:73], s[0:1], v[98:99] op_sel_hi:[1,0,1]
	v_lshlrev_b32_e32 v98, 16, v74
	v_and_b32_e32 v99, 0xffff0000, v74
	v_lshlrev_b32_e32 v74, 16, v70
	v_and_b32_e32 v75, 0xffff0000, v70
	v_add_f32_e32 v1, v105, v1
	v_pk_fma_f32 v[70:71], v[98:99], s[0:1], v[74:75] op_sel_hi:[1,0,1]
	s_nop 0
	v_add_f32_e32 v1, v70, v1
	v_add_f32_e32 v1, v71, v1
	v_add_f32_e32 v1, v72, v1
	v_add_f32_e32 v1, v73, v1
	v_add_f32_e32 v1, v106, v1
	v_add_f32_e32 v1, v107, v1
	v_add_f32_e32 v1, v112, v1
	v_add_f32_e32 v1, v113, v1
	v_add_f32_e32 v1, v100, v1
	v_add_f32_e32 v1, v101, v1
	v_add_f32_e32 v1, v102, v1
	v_add_f32_e32 v1, v103, v1
	v_add_f32_e32 v1, v96, v1
	v_add_f32_e32 v1, v97, v1
	v_add_f32_e32 v1, v94, v1
	v_add_f32_e32 v1, v95, v1
	v_add_f32_e32 v1, v92, v1
	v_add_f32_e32 v1, v93, v1
	v_add_f32_e32 v1, v90, v1
	v_add_f32_e32 v1, v91, v1
	v_add_f32_e32 v1, v88, v1
	v_add_f32_e32 v1, v89, v1
	v_add_f32_e32 v1, v84, v1
	v_add_f32_e32 v1, v85, v1
	v_add_f32_e32 v1, v86, v1
	v_add_f32_e32 v1, v87, v1
	v_add_f32_e32 v1, v82, v1
; __device__ __forceinline__ unsigned cvt_pk_bf16(float lo, float hi) { const f32x2v v = {lo, hi}; const b16x2v r = __builtin_convertvector(v, b16x2v); return __builtin_bit_cast(unsigned, r); }
; __device__ void ln_phase2(const bf16_t* __restrict__ mix, const float* __restrict__ Rf, const bf16_t* __restrict__ Rb, const float* __restrict__ gam, const float* __restrict__ bet, bf16_t* ob, float* of) {
;     ...
;         for (int o = 32; o; o >>= 1) s += __shfl_xor(s, o);
;         const float mean = s * (1.0f / 2048.0f);
;         float q = 0.f;
; #pragma unroll
;         for (int e = 0; e < 32; ++e) { const float dlt = v[e] - mean; q += dlt * dlt; }
; #pragma unroll
;         for (int o = 32; o; o >>= 1) q += __shfl_xor(q, o);
;         const float rstd = rsqrtf(q * (1.0f / 2048.0f) + 1e-5f);
; #pragma unroll
;         for (int j = 0; j < 4; ++j) {
;             const f32x4 g0 = *(const f32x4*)(gam + lane * 8 + 512 * j), g1 = *(const f32x4*)(gam + lane * 8 + 512 * j + 4);
;             const f32x4 b0 = *(const f32x4*)(bet + lane * 8 + 512 * j), b1 = *(const f32x4*)(bet + lane * 8 + 512 * j + 4);
;             f32x4 y0, y1;
; #pragma unroll
;             for (int e = 0; e < 4; ++e) { y0[e] = (v[8 * j + e] - mean) * rstd * g0[e] + b0[e]; y1[e] = (v[8 * j + 4 + e] - mean) * rstd * g1[e] + b1[e]; }
;             if (ob) { u32x4 w; w.x = cvt_pk_bf16(y0[0], y0[1]); w.y = cvt_pk_bf16(y0[2], y0[3]); w.z = cvt_pk_bf16(y1[0], y1[1]); w.w = cvt_pk_bf16(y1[2], y1[3]); *(u32x4*)(ob + ro + 512 * j) = w; }
	v_add_f32_e32 v1, v83, v1
	v_mov_b32_e32 v74, v1
	s_nop 1
	v_permlane32_swap_b32 v74, v1
	v_add_f32_e32 v1, v1, v74
	v_mov_b32_e32 v74, v1
	s_nop 1
	v_permlane16_swap_b32 v74, v1
	v_add_f32_e32 v1, v1, v74
	s_nop 1
	v_add_f32_dpp v1, v1, v1 quad_perm:[1,0,3,2] row_mask:0xf bank_mask:0xf
	s_nop 1
	v_add_f32_dpp v1, v1, v1 quad_perm:[2,3,0,1] row_mask:0xf bank_mask:0xf
	s_nop 1
	v_add_f32_dpp v1, v1, v1 row_half_mirror row_mask:0xf bank_mask:0xf
	s_nop 1
	v_add_f32_dpp v1, v1, v1 row_mirror row_mask:0xf bank_mask:0xf
	v_mul_f32_e32 v114, 0x3a000000, v1
	v_pk_add_f32 v[98:99], v[68:69], v[114:115] op_sel_hi:[1,0] neg_lo:[0,1] neg_hi:[0,1]
	v_pk_add_f32 v[104:105], v[104:105], v[114:115] op_sel_hi:[1,0] neg_lo:[0,1] neg_hi:[0,1]
	v_pk_mul_f32 v[68:69], v[98:99], v[98:99]
	v_pk_mul_f32 v[116:117], v[104:105], v[104:105]
	v_add_f32_e32 v1, v68, v69
	v_pk_add_f32 v[70:71], v[70:71], v[114:115] op_sel_hi:[1,0] neg_lo:[0,1] neg_hi:[0,1]
	v_add_f32_e32 v1, v116, v1
	v_pk_mul_f32 v[118:119], v[70:71], v[70:71]
	v_add_f32_e32 v1, v117, v1
	v_pk_add_f32 v[120:121], v[72:73], v[114:115] op_sel_hi:[1,0] neg_lo:[0,1] neg_hi:[0,1]
	v_add_f32_e32 v1, v118, v1
	v_pk_mul_f32 v[122:123], v[120:121], v[120:121]
	v_add_f32_e32 v1, v119, v1
	v_pk_add_f32 v[72:73], v[106:107], v[114:115] op_sel_hi:[1,0] neg_lo:[0,1] neg_hi:[0,1]
	v_add_f32_e32 v1, v122, v1
	v_pk_mul_f32 v[106:107], v[72:73], v[72:73]
	v_add_f32_e32 v1, v123, v1
	v_pk_add_f32 v[74:75], v[112:113], v[114:115] op_sel_hi:[1,0] neg_lo:[0,1] neg_hi:[0,1]
	v_add_f32_e32 v1, v106, v1
	v_pk_mul_f32 v[112:113], v[74:75], v[74:75]
	v_add_f32_e32 v1, v107, v1
	v_pk_add_f32 v[100:101], v[100:101], v[114:115] op_sel_hi:[1,0] neg_lo:[0,1] neg_hi:[0,1]
	v_add_f32_e32 v1, v112, v1
	v_pk_mul_f32 v[124:125], v[100:101], v[100:101]
	v_add_f32_e32 v1, v113, v1
	v_pk_add_f32 v[102:103], v[102:103], v[114:115] op_sel_hi:[1,0] neg_lo:[0,1] neg_hi:[0,1]
	v_add_f32_e32 v1, v124, v1
	v_pk_mul_f32 v[126:127], v[102:103], v[102:103]
	v_add_f32_e32 v1, v125, v1
	v_pk_add_f32 v[96:97], v[96:97], v[114:115] op_sel_hi:[1,0] neg_lo:[0,1] neg_hi:[0,1]
	v_add_f32_e32 v1, v126, v1
	v_pk_mul_f32 v[128:129], v[96:97], v[96:97]
	v_add_f32_e32 v1, v127, v1
	v_pk_add_f32 v[94:95], v[94:95], v[114:115] op_sel_hi:[1,0] neg_lo:[0,1] neg_hi:[0,1]
	v_add_f32_e32 v1, v128, v1
	v_pk_mul_f32 v[130:131], v[94:95], v[94:95]
	v_add_f32_e32 v1, v129, v1
	v_pk_add_f32 v[92:93], v[92:93], v[114:115] op_sel_hi:[1,0] neg_lo:[0,1] neg_hi:[0,1]
	v_add_f32_e32 v1, v130, v1
	v_pk_mul_f32 v[132:133], v[92:93], v[92:93]
	v_add_f32_e32 v1, v131, v1
	v_pk_add_f32 v[90:91], v[90:91], v[114:115] op_sel_hi:[1,0] neg_lo:[0,1] neg_hi:[0,1]
	v_add_f32_e32 v1, v132, v1
	v_pk_mul_f32 v[134:135], v[90:91], v[90:91]
	v_add_f32_e32 v1, v133, v1
	v_pk_add_f32 v[88:89], v[88:89], v[114:115] op_sel_hi:[1,0] neg_lo:[0,1] neg_hi:[0,1]
	v_add_f32_e32 v1, v134, v1
	v_pk_mul_f32 v[136:137], v[88:89], v[88:89]
	v_add_f32_e32 v1, v135, v1
	v_pk_add_f32 v[84:85], v[84:85], v[114:115] op_sel_hi:[1,0] neg_lo:[0,1] neg_hi:[0,1]
	v_add_f32_e32 v1, v136, v1
	v_pk_mul_f32 v[138:139], v[84:85], v[84:85]
	v_add_f32_e32 v1, v137, v1
	v_pk_add_f32 v[86:87], v[86:87], v[114:115] op_sel_hi:[1,0] neg_lo:[0,1] neg_hi:[0,1]
	v_add_f32_e32 v1, v138, v1
	v_pk_mul_f32 v[140:141], v[86:87], v[86:87]
	v_add_f32_e32 v1, v139, v1
	v_pk_add_f32 v[82:83], v[82:83], v[114:115] op_sel_hi:[1,0] neg_lo:[0,1] neg_hi:[0,1]
	v_add_f32_e32 v1, v140, v1
	v_pk_mul_f32 v[114:115], v[82:83], v[82:83]
	v_add_f32_e32 v1, v141, v1
	v_add_f32_e32 v1, v114, v1
	v_add_f32_e32 v1, v115, v1
	v_mov_b32_e32 v68, v1
	s_nop 1
	v_permlane32_swap_b32 v68, v1
	v_add_f32_e32 v1, v1, v68
	v_mov_b32_e32 v68, v1
	s_nop 1
	v_permlane16_swap_b32 v68, v1
	v_add_f32_e32 v1, v1, v68
	s_nop 1
	v_add_f32_dpp v1, v1, v1 quad_perm:[1,0,3,2] row_mask:0xf bank_mask:0xf
	s_nop 1
	v_add_f32_dpp v1, v1, v1 quad_perm:[2,3,0,1] row_mask:0xf bank_mask:0xf
	s_nop 1
	v_add_f32_dpp v1, v1, v1 row_half_mirror row_mask:0xf bank_mask:0xf
	s_nop 1
	v_add_f32_dpp v1, v1, v1 row_mirror row_mask:0xf bank_mask:0xf
	v_fmamk_f32 v1, v1, 0x3a000000, v213
	v_cmp_gt_f32_e32 vcc, s15, v1
	v_mul_f32_e32 v68, 0x4b800000, v1
	s_nop 0
	v_cndmask_b32_e32 v1, v1, v68, vcc
	v_rsq_f32_e32 v1, v1
	s_nop 0
	v_mul_f32_e32 v68, 0x45800000, v1
	v_cndmask_b32_e32 v106, v1, v68, vcc
	v_mov_b32_e32 v107, v106
	v_pk_mul_f32 v[68:69], v[70:71], v[106:107] op_sel_hi:[1,0]
	v_pk_mul_f32 v[70:71], v[120:121], v[106:107] op_sel_hi:[1,0]
	v_cndmask_b32_e64 v1, 0, 1, s[10:11]
	v_pk_fma_f32 v[68:69], v[4:5], v[68:69], v[8:9]
	v_pk_fma_f32 v[70:71], v[6:7], v[70:71], v[10:11]
	v_cmp_ne_u32_e64 s[0:1], 1, v1
	s_andn2_b64 vcc, exec, s[10:11]
	s_cbranch_vccnz .LBB0_68
	v_pk_mul_f32 v[98:99], v[98:99], v[106:107]
	v_pk_mul_f32 v[104:105], v[104:105], v[106:107]
	v_pk_fma_f32 v[98:99], v[12:13], v[98:99], v[16:17]
	v_pk_fma_f32 v[104:105], v[14:15], v[104:105], v[18:19]
	v_cvt_pk_bf16_f32 v112, v98, v99
	v_cvt_pk_bf16_f32 v113, v104, v105
	v_cvt_pk_bf16_f32 v114, v68, v69
	v_cvt_pk_bf16_f32 v115, v70, v71
	global_store_dwordx4 v[80:81], v[112:115], off
	v_lshlrev_b64 v[78:79], 2, v[78:79]
	s_cbranch_execnz .LBB0_60

; __device__ __forceinline__ float bflo(unsigned u) { return __uint_as_float(u << 16); }
; __device__ __forceinline__ float bfhi(unsigned u) { return __uint_as_float(u & 0xffff0000u); }
; __device__ void ln_phase2(const bf16_t* __restrict__ mix, const float* __restrict__ Rf, const bf16_t* __restrict__ Rb, const float* __restrict__ gam, const float* __restrict__ bet, bf16_t* ob, float* of) {
;     ...
;     for (int row = blockIdx.x * 8 + wid; row < T_TOK; row += gridDim.x * 8) {
;         const size_t ro = (size_t)row * DM + lane * 8;
;         float v[32]; float s = 0.f;
; #pragma unroll
;         for (int j = 0; j < 4; ++j) {
;             const u32x4 m = *(const u32x4*)(mix + ro + 512 * j);
;             float r[8];
;             if (Rf) { const f32x4 a = *(const f32x4*)(Rf + ro + 512 * j), b = *(const f32x4*)(Rf + ro + 512 * j + 4);
;                 r[0] = a[0]; r[1] = a[1]; r[2] = a[2]; r[3] = a[3]; r[4] = b[0]; r[5] = b[1]; r[6] = b[2]; r[7] = b[3]; }
;             else { const u32x4 rb = *(const u32x4*)(Rb + ro + 512 * j);
;                 r[0] = bflo(rb.x); r[1] = bfhi(rb.x); r[2] = bflo(rb.y); r[3] = bfhi(rb.y); r[4] = bflo(rb.z); r[5] = bfhi(rb.z); r[6] = bflo(rb.w); r[7] = bfhi(rb.w); }
;             v[8 * j + 0] = DN_ALPHA * r[0] + bflo(m.x); v[8 * j + 1] = DN_ALPHA * r[1] + bfhi(m.x); v[8 * j + 2] = DN_ALPHA * r[2] + bflo(m.y); v[8 * j + 3] = DN_ALPHA * r[3] + bfhi(m.y);
;             v[8 * j + 4] = DN_ALPHA * r[4] + bflo(m.z); v[8 * j + 5] = DN_ALPHA * r[5] + bfhi(m.z); v[8 * j + 6] = DN_ALPHA * r[6] + bflo(m.w); v[8 * j + 7] = DN_ALPHA * r[7] + bfhi(m.w);
; #pragma unroll
;             for (int e = 0; e < 8; ++e) s += v[8 * j + e];
;         }
; #pragma unroll
;         for (int o = 32; o; o >>= 1) s += __shfl_xor(s, o);
;         const float mean = s * (1.0f / 2048.0f);
.LBB0_93:
	v_ashrrev_i32_e32 v1, 31, v0
	v_lshlrev_b64 v[68:69], 11, v[0:1]
	v_or_b32_e32 v68, v68, v100
	v_lshlrev_b64 v[106:107], 1, v[68:69]
	v_lshl_add_u64 v[68:69], v[68:69], 2, s[72:73]
	v_add_co_u32_e32 v102, vcc, s9, v68
	v_lshl_add_u64 v[70:71], s[26:27], 0, v[106:107]
	v_lshl_add_u64 v[76:77], v[68:69], 0, s[12:13]
	v_addc_co_u32_e32 v103, vcc, 0, v69, vcc
	global_load_dwordx4 v[118:121], v[70:71], off nt
	global_load_dwordx4 v[122:125], v[68:69], off nt
	global_load_dwordx4 v[110:113], v[68:69], off offset:16 nt
	global_load_dwordx4 v[88:91], v[70:71], off offset:1024 nt
	global_load_dwordx4 v[92:95], v[68:69], off offset:2048 nt
	global_load_dwordx4 v[96:99], v[68:69], off offset:2064 nt
	global_load_dwordx4 v[72:75], v[70:71], off offset:2048 nt
	global_load_dwordx4 v[80:83], v[102:103], off nt
	global_load_dwordx4 v[84:87], v[76:77], off offset:16 nt
	s_nop 0
	global_load_dwordx4 v[76:79], v[70:71], off offset:3072 nt
	v_lshl_add_u64 v[104:105], v[68:69], 0, s[16:17]
	global_load_dwordx4 v[68:71], v[102:103], off offset:2048 nt
	s_nop 0
	global_load_dwordx4 v[102:105], v[104:105], off offset:16 nt
	v_add_u32_e32 v0, s8, v0
	s_waitcnt vmcnt(0)
	v_and_b32_e32 v109, 0xffff0000, v78
	v_lshlrev_b32_e32 v108, 16, v78
	v_pk_fma_f32 v[102:103], v[102:103], s[22:23], v[108:109] op_sel_hi:[1,0,1]
	v_and_b32_e32 v109, 0xffff0000, v79
	v_lshlrev_b32_e32 v108, 16, v79
	v_lshl_add_u64 v[78:79], s[64:65], 0, v[106:107]
	v_lshlrev_b32_e32 v106, 16, v121
	v_and_b32_e32 v107, 0xffff0000, v121
	v_pk_fma_f32 v[106:107], v[112:113], s[22:23], v[106:107] op_sel_hi:[1,0,1]
	v_lshlrev_b32_e32 v112, 16, v120
	v_and_b32_e32 v113, 0xffff0000, v120
	v_pk_fma_f32 v[110:111], v[110:111], s[22:23], v[112:113] op_sel_hi:[1,0,1]
	v_lshlrev_b32_e32 v112, 16, v118
	v_and_b32_e32 v113, 0xffff0000, v118
	v_pk_fma_f32 v[112:113], v[122:123], s[22:23], v[112:113] op_sel_hi:[1,0,1]
	v_pk_fma_f32 v[104:105], v[104:105], s[22:23], v[108:109] op_sel_hi:[1,0,1]
	v_lshlrev_b32_e32 v108, 16, v119
	v_and_b32_e32 v109, 0xffff0000, v119
	v_add_f32_e32 v1, 0, v112
	v_pk_fma_f32 v[108:109], v[124:125], s[22:23], v[108:109] op_sel_hi:[1,0,1]
	v_add_f32_e32 v1, v113, v1
	v_add_f32_e32 v1, v108, v1
	v_add_f32_e32 v1, v109, v1
	v_lshlrev_b32_e32 v118, 16, v91
	v_and_b32_e32 v119, 0xffff0000, v91
	v_add_f32_e32 v1, v110, v1
	v_pk_fma_f32 v[98:99], v[98:99], s[22:23], v[118:119] op_sel_hi:[1,0,1]
	v_lshlrev_b32_e32 v118, 16, v89
	v_and_b32_e32 v119, 0xffff0000, v89
	v_add_f32_e32 v1, v111, v1
	v_pk_fma_f32 v[94:95], v[94:95], s[22:23], v[118:119] op_sel_hi:[1,0,1]
	v_lshlrev_b32_e32 v118, 16, v90
	v_and_b32_e32 v119, 0xffff0000, v90
	v_add_f32_e32 v1, v106, v1
	v_pk_fma_f32 v[90:91], v[96:97], s[22:23], v[118:119] op_sel_hi:[1,0,1]
	v_lshlrev_b32_e32 v96, 16, v88
	v_and_b32_e32 v97, 0xffff0000, v88
	v_add_f32_e32 v1, v107, v1
	v_pk_fma_f32 v[88:89], v[92:93], s[22:23], v[96:97] op_sel_hi:[1,0,1]
	v_lshlrev_b32_e32 v92, 16, v75
	v_add_f32_e32 v1, v1, v88
	v_add_f32_e32 v1, v89, v1
	v_add_f32_e32 v1, v94, v1
	v_add_f32_e32 v1, v95, v1
	v_and_b32_e32 v93, 0xffff0000, v75
	v_add_f32_e32 v1, v90, v1
	v_pk_fma_f32 v[86:87], v[86:87], s[22:23], v[92:93] op_sel_hi:[1,0,1]
	v_lshlrev_b32_e32 v92, 16, v73
	v_and_b32_e32 v93, 0xffff0000, v73
	v_add_f32_e32 v1, v91, v1
	v_pk_fma_f32 v[82:83], v[82:83], s[22:23], v[92:93] op_sel_hi:[1,0,1]
	v_lshlrev_b32_e32 v92, 16, v74
	v_and_b32_e32 v93, 0xffff0000, v74
	v_add_f32_e32 v1, v98, v1
	v_pk_fma_f32 v[74:75], v[84:85], s[22:23], v[92:93] op_sel_hi:[1,0,1]
	v_lshlrev_b32_e32 v84, 16, v72
	v_and_b32_e32 v85, 0xffff0000, v72
	v_add_f32_e32 v1, v99, v1
	v_pk_fma_f32 v[72:73], v[80:81], s[22:23], v[84:85] op_sel_hi:[1,0,1]
	v_lshlrev_b32_e32 v80, 16, v77
	v_add_f32_e32 v1, v1, v72
	v_add_f32_e32 v1, v73, v1
	v_add_f32_e32 v1, v82, v1
	v_add_f32_e32 v1, v83, v1
	v_add_f32_e32 v1, v74, v1
	v_add_f32_e32 v1, v75, v1
	v_and_b32_e32 v81, 0xffff0000, v77
	v_add_f32_e32 v1, v86, v1
	v_pk_fma_f32 v[70:71], v[70:71], s[22:23], v[80:81] op_sel_hi:[1,0,1]
	v_lshlrev_b32_e32 v80, 16, v76
	v_and_b32_e32 v81, 0xffff0000, v76
	v_add_f32_e32 v1, v87, v1
	v_pk_fma_f32 v[68:69], v[68:69], s[22:23], v[80:81] op_sel_hi:[1,0,1]
	s_nop 0
	v_add_f32_e32 v1, v1, v68
	v_add_f32_e32 v1, v69, v1
	v_add_f32_e32 v1, v70, v1
	v_add_f32_e32 v1, v71, v1
	v_add_f32_e32 v1, v102, v1
	v_add_f32_e32 v1, v103, v1
	v_add_f32_e32 v1, v104, v1
	v_add_f32_e32 v1, v105, v1
	v_mov_b32_e32 v76, v1
	s_nop 1
	v_permlane32_swap_b32 v76, v1
	v_add_f32_e32 v1, v1, v76
	v_mov_b32_e32 v76, v1
	s_nop 1
	v_permlane16_swap_b32 v76, v1
	v_add_f32_e32 v1, v1, v76
	s_nop 1
	v_add_f32_dpp v1, v1, v1 quad_perm:[1,0,3,2] row_mask:0xf bank_mask:0xf
	s_nop 1
	v_add_f32_dpp v1, v1, v1 quad_perm:[2,3,0,1] row_mask:0xf bank_mask:0xf
	s_nop 1
	v_add_f32_dpp v1, v1, v1 row_half_mirror row_mask:0xf bank_mask:0xf
	s_nop 1
	v_add_f32_dpp v1, v1, v1 row_mirror row_mask:0xf bank_mask:0xf
	v_mul_f32_e32 v92, 0x3a000000, v1
	v_pk_add_f32 v[96:97], v[112:113], v[92:93] op_sel_hi:[1,0] neg_lo:[0,1] neg_hi:[0,1]
	v_pk_add_f32 v[108:109], v[108:109], v[92:93] op_sel_hi:[1,0] neg_lo:[0,1] neg_hi:[0,1]
	v_pk_mul_f32 v[112:113], v[96:97], v[96:97]
	v_pk_mul_f32 v[118:119], v[108:109], v[108:109]
	v_add_f32_e32 v1, v112, v113
	v_pk_add_f32 v[110:111], v[110:111], v[92:93] op_sel_hi:[1,0] neg_lo:[0,1] neg_hi:[0,1]
	v_add_f32_e32 v1, v118, v1
	v_pk_mul_f32 v[120:121], v[110:111], v[110:111]
	v_add_f32_e32 v1, v119, v1
	v_pk_add_f32 v[106:107], v[106:107], v[92:93] op_sel_hi:[1,0] neg_lo:[0,1] neg_hi:[0,1]
	v_add_f32_e32 v1, v120, v1
	v_pk_mul_f32 v[122:123], v[106:107], v[106:107]
	v_add_f32_e32 v1, v121, v1
; __device__ __forceinline__ unsigned cvt_pk_bf16(float lo, float hi) { const f32x2v v = {lo, hi}; const b16x2v r = __builtin_convertvector(v, b16x2v); return __builtin_bit_cast(unsigned, r); }
; __device__ void ln_phase2(const bf16_t* __restrict__ mix, const float* __restrict__ Rf, const bf16_t* __restrict__ Rb, const float* __restrict__ gam, const float* __restrict__ bet, bf16_t* ob, float* of) {
;     ...
;         float q = 0.f;
; #pragma unroll
;         for (int e = 0; e < 32; ++e) { const float dlt = v[e] - mean; q += dlt * dlt; }
; #pragma unroll
;         for (int o = 32; o; o >>= 1) q += __shfl_xor(q, o);
;         const float rstd = rsqrtf(q * (1.0f / 2048.0f) + 1e-5f);
; #pragma unroll
;         for (int j = 0; j < 4; ++j) {
;             const f32x4 g0 = *(const f32x4*)(gam + lane * 8 + 512 * j), g1 = *(const f32x4*)(gam + lane * 8 + 512 * j + 4);
;             const f32x4 b0 = *(const f32x4*)(bet + lane * 8 + 512 * j), b1 = *(const f32x4*)(bet + lane * 8 + 512 * j + 4);
;             f32x4 y0, y1;
; #pragma unroll
;             for (int e = 0; e < 4; ++e) { y0[e] = (v[8 * j + e] - mean) * rstd * g0[e] + b0[e]; y1[e] = (v[8 * j + 4 + e] - mean) * rstd * g1[e] + b1[e]; }
;             if (ob) { u32x4 w; w.x = cvt_pk_bf16(y0[0], y0[1]); w.y = cvt_pk_bf16(y0[2], y0[3]); w.z = cvt_pk_bf16(y1[0], y1[1]); w.w = cvt_pk_bf16(y1[2], y1[3]); *(u32x4*)(ob + ro + 512 * j) = w; }
;             else { *(f32x4*)(of + ro + 512 * j) = y0; *(f32x4*)(of + ro + 512 * j + 4) = y1; }
;         }
	v_pk_add_f32 v[124:125], v[88:89], v[92:93] op_sel_hi:[1,0] neg_lo:[0,1] neg_hi:[0,1]
	v_add_f32_e32 v1, v122, v1
	v_pk_mul_f32 v[88:89], v[124:125], v[124:125]
	v_add_f32_e32 v1, v123, v1
	v_pk_add_f32 v[94:95], v[94:95], v[92:93] op_sel_hi:[1,0] neg_lo:[0,1] neg_hi:[0,1]
	v_add_f32_e32 v1, v88, v1
	v_pk_mul_f32 v[126:127], v[94:95], v[94:95]
	v_add_f32_e32 v1, v89, v1
	v_pk_add_f32 v[90:91], v[90:91], v[92:93] op_sel_hi:[1,0] neg_lo:[0,1] neg_hi:[0,1]
	v_add_f32_e32 v1, v126, v1
	v_pk_mul_f32 v[128:129], v[90:91], v[90:91]
	v_add_f32_e32 v1, v127, v1
	v_pk_add_f32 v[98:99], v[98:99], v[92:93] op_sel_hi:[1,0] neg_lo:[0,1] neg_hi:[0,1]
	v_add_f32_e32 v1, v128, v1
	v_pk_mul_f32 v[130:131], v[98:99], v[98:99]
	v_add_f32_e32 v1, v129, v1
	v_pk_add_f32 v[80:81], v[72:73], v[92:93] op_sel_hi:[1,0] neg_lo:[0,1] neg_hi:[0,1]
	v_add_f32_e32 v1, v130, v1
	v_pk_mul_f32 v[132:133], v[80:81], v[80:81]
	v_add_f32_e32 v1, v131, v1
	v_pk_add_f32 v[76:77], v[82:83], v[92:93] op_sel_hi:[1,0] neg_lo:[0,1] neg_hi:[0,1]
	v_add_f32_e32 v1, v132, v1
	v_pk_mul_f32 v[134:135], v[76:77], v[76:77]
	v_add_f32_e32 v1, v133, v1
	v_pk_add_f32 v[84:85], v[74:75], v[92:93] op_sel_hi:[1,0] neg_lo:[0,1] neg_hi:[0,1]
	v_add_f32_e32 v1, v134, v1
	v_pk_mul_f32 v[136:137], v[84:85], v[84:85]
	v_add_f32_e32 v1, v135, v1
	v_pk_add_f32 v[82:83], v[86:87], v[92:93] op_sel_hi:[1,0] neg_lo:[0,1] neg_hi:[0,1]
	v_add_f32_e32 v1, v136, v1
	v_pk_mul_f32 v[86:87], v[82:83], v[82:83]
	v_add_f32_e32 v1, v137, v1
	v_pk_add_f32 v[68:69], v[68:69], v[92:93] op_sel_hi:[1,0] neg_lo:[0,1] neg_hi:[0,1]
	v_add_f32_e32 v1, v86, v1
	v_pk_mul_f32 v[138:139], v[68:69], v[68:69]
	v_add_f32_e32 v1, v87, v1
	v_pk_add_f32 v[70:71], v[70:71], v[92:93] op_sel_hi:[1,0] neg_lo:[0,1] neg_hi:[0,1]
	v_add_f32_e32 v1, v138, v1
	v_pk_mul_f32 v[140:141], v[70:71], v[70:71]
	v_add_f32_e32 v1, v139, v1
	v_pk_add_f32 v[74:75], v[102:103], v[92:93] op_sel_hi:[1,0] neg_lo:[0,1] neg_hi:[0,1]
	v_add_f32_e32 v1, v140, v1
	v_pk_add_f32 v[72:73], v[104:105], v[92:93] op_sel_hi:[1,0] neg_lo:[0,1] neg_hi:[0,1]
	v_pk_mul_f32 v[92:93], v[74:75], v[74:75]
	v_add_f32_e32 v1, v141, v1
	v_add_f32_e32 v1, v92, v1
	v_pk_mul_f32 v[104:105], v[72:73], v[72:73]
	v_add_f32_e32 v1, v93, v1
	v_add_f32_e32 v1, v104, v1
	v_add_f32_e32 v1, v105, v1
	v_mov_b32_e32 v86, v1
	s_nop 1
	v_permlane32_swap_b32 v86, v1
	v_add_f32_e32 v1, v1, v86
	v_mov_b32_e32 v86, v1
	s_nop 1
	v_permlane16_swap_b32 v86, v1
	v_add_f32_e32 v1, v1, v86
	s_nop 1
	v_add_f32_dpp v1, v1, v1 quad_perm:[1,0,3,2] row_mask:0xf bank_mask:0xf
	s_nop 1
	v_add_f32_dpp v1, v1, v1 quad_perm:[2,3,0,1] row_mask:0xf bank_mask:0xf
	s_nop 1
	v_add_f32_dpp v1, v1, v1 row_half_mirror row_mask:0xf bank_mask:0xf
	s_nop 1
	v_add_f32_dpp v1, v1, v1 row_mirror row_mask:0xf bank_mask:0xf
	v_fmamk_f32 v1, v1, 0x3a000000, v213
	v_cmp_gt_f32_e32 vcc, s15, v1
	v_mul_f32_e32 v86, 0x4b800000, v1
	s_nop 0
	v_cndmask_b32_e32 v1, v1, v86, vcc
	v_rsq_f32_e32 v1, v1
	s_nop 0
	v_mul_f32_e32 v86, 0x45800000, v1
	v_cndmask_b32_e32 v92, v1, v86, vcc
	v_pk_mul_f32 v[86:87], v[96:97], v[92:93] op_sel_hi:[1,0]
	v_pk_mul_f32 v[88:89], v[110:111], v[92:93] op_sel_hi:[1,0]
	v_pk_mul_f32 v[96:97], v[108:109], v[92:93] op_sel_hi:[1,0]
	v_pk_mul_f32 v[102:103], v[106:107], v[92:93] op_sel_hi:[1,0]
	v_pk_fma_f32 v[86:87], v[4:5], v[86:87], v[8:9]
	v_pk_fma_f32 v[88:89], v[12:13], v[88:89], v[16:17]
	v_pk_fma_f32 v[96:97], v[6:7], v[96:97], v[10:11]
	v_pk_fma_f32 v[102:103], v[14:15], v[102:103], v[18:19]
	v_cvt_pk_bf16_f32 v86, v86, v87
	v_cvt_pk_bf16_f32 v87, v96, v97
	v_cvt_pk_bf16_f32 v88, v88, v89
	v_cvt_pk_bf16_f32 v89, v102, v103
	global_store_dwordx4 v[78:79], v[86:89], off
	v_pk_mul_f32 v[80:81], v[80:81], v[92:93] op_sel_hi:[1,0]
	v_pk_mul_f32 v[84:85], v[84:85], v[92:93] op_sel_hi:[1,0]
	v_pk_mul_f32 v[86:87], v[124:125], v[92:93] op_sel_hi:[1,0]
	v_pk_mul_f32 v[88:89], v[90:91], v[92:93] op_sel_hi:[1,0]
	v_pk_mul_f32 v[90:91], v[94:95], v[92:93] op_sel_hi:[1,0]
	v_pk_mul_f32 v[94:95], v[98:99], v[92:93] op_sel_hi:[1,0]
	v_pk_fma_f32 v[86:87], v[20:21], v[86:87], v[24:25]
	v_pk_fma_f32 v[88:89], v[28:29], v[88:89], v[32:33]
	v_pk_fma_f32 v[90:91], v[22:23], v[90:91], v[26:27]
	v_pk_fma_f32 v[94:95], v[30:31], v[94:95], v[34:35]
	v_cvt_pk_bf16_f32 v86, v86, v87
	v_cvt_pk_bf16_f32 v87, v90, v91
	v_cvt_pk_bf16_f32 v88, v88, v89
	v_cvt_pk_bf16_f32 v89, v94, v95
	v_pk_mul_f32 v[76:77], v[76:77], v[92:93] op_sel_hi:[1,0]
	v_pk_mul_f32 v[82:83], v[82:83], v[92:93] op_sel_hi:[1,0]
	v_pk_mul_f32 v[68:69], v[68:69], v[92:93] op_sel_hi:[1,0]
	v_pk_mul_f32 v[74:75], v[74:75], v[92:93] op_sel_hi:[1,0]
	v_pk_mul_f32 v[70:71], v[70:71], v[92:93] op_sel_hi:[1,0]
	v_pk_mul_f32 v[72:73], v[72:73], v[92:93] op_sel_hi:[1,0]
	global_store_dwordx4 v[78:79], v[86:89], off offset:1024
	v_pk_fma_f32 v[80:81], v[36:37], v[80:81], v[44:45]
	v_pk_fma_f32 v[84:85], v[40:41], v[84:85], v[48:49]
	v_pk_fma_f32 v[76:77], v[38:39], v[76:77], v[46:47]
	v_pk_fma_f32 v[86:87], v[42:43], v[82:83], v[50:51]
	v_pk_fma_f32 v[68:69], v[52:53], v[68:69], v[60:61]
	v_pk_fma_f32 v[74:75], v[56:57], v[74:75], v[64:65]
	v_pk_fma_f32 v[70:71], v[54:55], v[70:71], v[62:63]
	v_pk_fma_f32 v[72:73], v[58:59], v[72:73], v[66:67]
	v_cmp_lt_i32_e32 vcc, s18, v0
	v_cvt_pk_bf16_f32 v80, v80, v81
	v_cvt_pk_bf16_f32 v81, v76, v77
	v_cvt_pk_bf16_f32 v82, v84, v85
	v_cvt_pk_bf16_f32 v83, v86, v87
	v_cvt_pk_bf16_f32 v68, v68, v69
	v_cvt_pk_bf16_f32 v69, v70, v71
	v_cvt_pk_bf16_f32 v70, v74, v75
	v_cvt_pk_bf16_f32 v71, v72, v73
	s_or_b64 s[2:3], vcc, s[2:3]
	global_store_dwordx4 v[78:79], v[80:83], off offset:2048
	global_store_dwordx4 v[78:79], v[68:71], off offset:3072
	s_andn2_b64 exec, exec, s[2:3]
	s_cbranch_execnz .LBB0_93

; __device__ __forceinline__ float bflo(unsigned u) { return __uint_as_float(u << 16); }
; __device__ __forceinline__ float bfhi(unsigned u) { return __uint_as_float(u & 0xffff0000u); }
; __device__ __forceinline__ float silu_f(float v) { return v / (1.0f + fexp2(-v * LOG2E)); }
; __device__ void merge_phase(const Params& p) {
;     ...
;         { const int hh = lane >> 4, sub = lane & 15;
;           const bf16_t* src = og + (size_t)tok * 1024 + hh * 256 + sub * 16;
;           const u32x4 a = *(const u32x4*)src, b = *(const u32x4*)(src + 8);
;           float xv[16];
; #pragma unroll
;           for (int j = 0; j < 4; ++j) { xv[2 * j] = bflo(a[j]); xv[2 * j + 1] = bfhi(a[j]); xv[8 + 2 * j] = bflo(b[j]); xv[8 + 2 * j + 1] = bfhi(b[j]); }
;           float s = 0.f;
; #pragma unroll
;           for (int j = 0; j < 16; ++j) s += xv[j];
;           s += __shfl_xor(s, 1); s += __shfl_xor(s, 2); s += __shfl_xor(s, 4); s += __shfl_xor(s, 8);
;           const float mean = s * (1.0f / 256.0f);
;           float q = 0.f;
; #pragma unroll
;           for (int j = 0; j < 16; ++j) { const float dlt = xv[j] - mean; q += dlt * dlt; }
;           q += __shfl_xor(q, 1); q += __shfl_xor(q, 2); q += __shfl_xor(q, 4); q += __shfl_xor(q, 8);
;           const float rstd = rsqrtf(q * (1.0f / 256.0f) + 1e-5f);
;           const bf16_t* rgp = h + (size_t)tok * HC + 2048 + hh * 256 + sub * 16;
;           const u32x4 ra = *(const u32x4*)rgp, rb = *(const u32x4*)(rgp + 8);
;           const float* ngp = p.norm_g + hh * 256 + sub * 16;
;           float ov[16];
; #pragma unroll
;           for (int j4 = 0; j4 < 4; ++j4) { const f32x4 ng = *(const f32x4*)(ngp + 4 * j4);
; #pragma unroll
;               for (int j = 0; j < 4; ++j) { const int e = 4 * j4 + j; const unsigned rw = (e < 8) ? ra[e >> 1] : rb[(e - 8) >> 1]; const float rv = (e & 1) ? bfhi(rw) : bflo(rw);
;                   ov[e] = (xv[e] - mean) * rstd * ng[j] * silu_f(rv); } }
.LBB0_100:
	v_ashrrev_i32_e32 v1, 31, v0
	v_lshlrev_b64 v[50:51], 11, v[0:1]
	v_lshl_add_u64 v[4:5], v[36:37], 0, v[50:51]
	global_load_dwordx4 v[24:27], v[4:5], off nt
	global_load_dwordx4 v[32:35], v[4:5], off offset:16 nt
	v_mov_b64_e32 v[4:5], s[92:93]
	v_mad_i64_i32 v[52:53], s[6:7], v0, s48, v[4:5]
	v_lshl_add_u64 v[4:5], v[52:53], 0, v[2:3]
	v_mov_b32_e32 v41, v3
	v_lshl_add_u64 v[4:5], v[4:5], 0, v[40:41]
	s_mov_b64 s[6:7], 0xd101000
	v_lshl_add_u64 v[6:7], v[4:5], 0, s[6:7]
	s_mov_b32 s6, 0xd101000
	v_add_co_u32_e32 v4, vcc, s6, v4
	s_waitcnt vmcnt(0)
	v_lshlrev_b32_e32 v58, 16, v27
	v_addc_co_u32_e32 v5, vcc, 0, v5, vcc
	global_load_dwordx4 v[28:31], v[4:5], off nt
	s_nop 0
	global_load_dwordx4 v[4:7], v[6:7], off offset:16 nt
	s_nop 0
	global_load_dwordx4 v[8:11], v[38:39], off offset:48
	global_load_dwordx4 v[12:15], v[38:39], off offset:32
	global_load_dwordx4 v[20:23], v[38:39], off
	global_load_dwordx4 v[16:19], v[38:39], off offset:16
	v_and_b32_e32 v59, 0xffff0000, v27
	v_lshlrev_b32_e32 v56, 16, v35
	v_and_b32_e32 v57, 0xffff0000, v35
	v_and_b32_e32 v61, 0xffff0000, v34
	v_and_b32_e32 v63, 0xffff0000, v26
	v_and_b32_e32 v65, 0xffff0000, v33
	v_lshlrev_b32_e32 v68, 16, v25
	v_and_b32_e32 v69, 0xffff0000, v25
	v_lshlrev_b32_e32 v70, 16, v32
	v_and_b32_e32 v71, 0xffff0000, v32
	s_waitcnt vmcnt(0)
	v_lshlrev_b32_e32 v27, 16, v31
	v_and_b32_e32 v31, 0xffff0000, v31
	v_mul_f32_e32 v35, 0xbfb8aa3b, v27
	v_exp_f32_e32 v54, v35
	v_mul_f32_e32 v35, 0xbfb8aa3b, v31
	v_exp_f32_e32 v55, v35
	s_nop 0
	v_pk_add_f32 v[54:55], v[54:55], 1.0 op_sel_hi:[1,0]
	s_nop 0
	v_div_scale_f32 v35, s[6:7], v55, v55, v31
	v_rcp_f32_e32 v43, v35
	s_nop 0
	v_fma_f32 v47, -v35, v43, 1.0
	v_fmac_f32_e32 v43, v47, v43
	v_div_scale_f32 v47, vcc, v31, v55, v31
	v_mul_f32_e32 v49, v47, v43
	v_fma_f32 v60, -v35, v49, v47
	v_fmac_f32_e32 v49, v60, v43
	v_fma_f32 v35, -v35, v49, v47
	v_div_fmas_f32 v35, v35, v43, v49
	v_div_fixup_f32 v55, v35, v55, v31
	v_div_scale_f32 v31, s[6:7], v54, v54, v27
	v_rcp_f32_e32 v35, v31
	v_lshlrev_b32_e32 v60, 16, v34
	v_fma_f32 v43, -v31, v35, 1.0
	v_fmac_f32_e32 v35, v43, v35
	v_div_scale_f32 v43, vcc, v27, v54, v27
	v_mul_f32_e32 v47, v43, v35
	v_fma_f32 v49, -v31, v47, v43
	v_fmac_f32_e32 v47, v49, v35
	v_fma_f32 v31, -v31, v47, v43
	v_div_fmas_f32 v31, v31, v35, v47
	v_div_fixup_f32 v54, v31, v54, v27
	v_lshlrev_b32_e32 v27, 16, v6
	v_and_b32_e32 v6, 0xffff0000, v6
	v_mul_f32_e32 v31, 0xbfb8aa3b, v27
	v_exp_f32_e32 v34, v31
	v_mul_f32_e32 v31, 0xbfb8aa3b, v6
	v_exp_f32_e32 v35, v31
	s_nop 0
	v_pk_add_f32 v[34:35], v[34:35], 1.0 op_sel_hi:[1,0]
	s_nop 0
	v_div_scale_f32 v31, s[6:7], v35, v35, v6
	v_rcp_f32_e32 v43, v31
	s_nop 0
	v_fma_f32 v47, -v31, v43, 1.0
	v_fmac_f32_e32 v43, v47, v43
	v_div_scale_f32 v47, vcc, v6, v35, v6
	v_mul_f32_e32 v49, v47, v43
	v_fma_f32 v62, -v31, v49, v47
	v_fmac_f32_e32 v49, v62, v43
	v_fma_f32 v31, -v31, v49, v47
	v_div_fmas_f32 v31, v31, v43, v49
	v_div_fixup_f32 v35, v31, v35, v6
	v_div_scale_f32 v6, s[6:7], v34, v34, v27
	v_rcp_f32_e32 v31, v6
	v_lshlrev_b32_e32 v62, 16, v26
	v_fma_f32 v43, -v6, v31, 1.0
	v_fmac_f32_e32 v31, v43, v31
	v_div_scale_f32 v43, vcc, v27, v34, v27
	v_mul_f32_e32 v47, v43, v31
	v_fma_f32 v49, -v6, v47, v43
	v_fmac_f32_e32 v47, v49, v31
	v_fma_f32 v6, -v6, v47, v43
	v_div_fmas_f32 v6, v6, v31, v47
	v_div_fixup_f32 v34, v6, v34, v27
	v_lshlrev_b32_e32 v6, 16, v30
	v_and_b32_e32 v30, 0xffff0000, v30
	v_mul_f32_e32 v26, 0xbfb8aa3b, v6
	v_mul_f32_e32 v27, 0xbfb8aa3b, v30
	v_exp_f32_e32 v26, v26
	v_exp_f32_e32 v27, v27
	s_nop 0
	v_pk_add_f32 v[26:27], v[26:27], 1.0 op_sel_hi:[1,0]
	s_nop 0
	v_div_scale_f32 v31, s[6:7], v27, v27, v30
	v_rcp_f32_e32 v43, v31
	s_nop 0
	v_fma_f32 v47, -v31, v43, 1.0
	v_fmac_f32_e32 v43, v47, v43
	v_div_scale_f32 v47, vcc, v30, v27, v30
	v_mul_f32_e32 v49, v47, v43
	v_fma_f32 v64, -v31, v49, v47
	v_fmac_f32_e32 v49, v64, v43
	v_fma_f32 v31, -v31, v49, v47
	v_div_fmas_f32 v31, v31, v43, v49
	v_div_fixup_f32 v27, v31, v27, v30
	v_div_scale_f32 v30, s[6:7], v26, v26, v6
	v_rcp_f32_e32 v31, v30
	v_lshlrev_b32_e32 v64, 16, v33
	v_fma_f32 v43, -v30, v31, 1.0
	v_fmac_f32_e32 v31, v43, v31
	v_div_scale_f32 v43, vcc, v6, v26, v6
	v_mul_f32_e32 v47, v43, v31
	v_fma_f32 v49, -v30, v47, v43
	v_fmac_f32_e32 v47, v49, v31
	v_fma_f32 v30, -v30, v47, v43
	v_div_fmas_f32 v30, v30, v31, v47
	v_div_fixup_f32 v26, v30, v26, v6
	v_lshlrev_b32_e32 v6, 16, v5
	v_and_b32_e32 v5, 0xffff0000, v5
	v_mul_f32_e32 v30, 0xbfb8aa3b, v6
	v_mul_f32_e32 v31, 0xbfb8aa3b, v5
	v_exp_f32_e32 v30, v30
	v_exp_f32_e32 v31, v31
	s_nop 0
	v_pk_add_f32 v[30:31], v[30:31], 1.0 op_sel_hi:[1,0]
	s_nop 0
	v_div_scale_f32 v33, s[6:7], v31, v31, v5
	v_rcp_f32_e32 v43, v33
	s_nop 0
	v_fma_f32 v47, -v33, v43, 1.0
	v_fmac_f32_e32 v43, v47, v43
	v_div_scale_f32 v47, vcc, v5, v31, v5
	v_mul_f32_e32 v49, v47, v43
	v_fma_f32 v66, -v33, v49, v47
	v_fmac_f32_e32 v49, v66, v43
	v_fma_f32 v33, -v33, v49, v47
	v_div_fmas_f32 v33, v33, v43, v49
	v_div_fixup_f32 v31, v33, v31, v5
	v_div_scale_f32 v5, s[6:7], v30, v30, v6
	v_rcp_f32_e32 v33, v5
	s_nop 0
	v_fma_f32 v43, -v5, v33, 1.0
	v_fmac_f32_e32 v33, v43, v33
	v_div_scale_f32 v43, vcc, v6, v30, v6
	v_mul_f32_e32 v47, v43, v33
	v_fma_f32 v49, -v5, v47, v43
	v_fmac_f32_e32 v47, v49, v33
	v_fma_f32 v5, -v5, v47, v43
	v_div_fmas_f32 v5, v5, v33, v47
	v_div_fixup_f32 v30, v5, v30, v6
	v_lshlrev_b32_e32 v5, 16, v29
	v_and_b32_e32 v6, 0xffff0000, v29
	v_mul_f32_e32 v25, 0xbfb8aa3b, v5
	v_exp_f32_e32 v66, v25
	v_mul_f32_e32 v25, 0xbfb8aa3b, v6
	v_exp_f32_e32 v67, v25
	s_nop 0
	v_pk_add_f32 v[66:67], v[66:67], 1.0 op_sel_hi:[1,0]
	s_nop 0
; __device__ __forceinline__ float bflo(unsigned u) { return __uint_as_float(u << 16); }
; __device__ __forceinline__ float bfhi(unsigned u) { return __uint_as_float(u & 0xffff0000u); }
; __device__ __forceinline__ float silu_f(float v) { return v / (1.0f + fexp2(-v * LOG2E)); }
; __device__ void merge_phase(const Params& p) {
;     ...
;           float s = 0.f;
; #pragma unroll
;           for (int j = 0; j < 16; ++j) s += xv[j];
;           s += __shfl_xor(s, 1); s += __shfl_xor(s, 2); s += __shfl_xor(s, 4); s += __shfl_xor(s, 8);
;           const float mean = s * (1.0f / 256.0f);
;           float q = 0.f;
; #pragma unroll
;           for (int j = 0; j < 16; ++j) { const float dlt = xv[j] - mean; q += dlt * dlt; }
;           q += __shfl_xor(q, 1); q += __shfl_xor(q, 2); q += __shfl_xor(q, 4); q += __shfl_xor(q, 8);
;           const float rstd = rsqrtf(q * (1.0f / 256.0f) + 1e-5f);
;           const bf16_t* rgp = h + (size_t)tok * HC + 2048 + hh * 256 + sub * 16;
;           const u32x4 ra = *(const u32x4*)rgp, rb = *(const u32x4*)(rgp + 8);
;           const float* ngp = p.norm_g + hh * 256 + sub * 16;
;           float ov[16];
; #pragma unroll
;           for (int j4 = 0; j4 < 4; ++j4) { const f32x4 ng = *(const f32x4*)(ngp + 4 * j4);
; #pragma unroll
;               for (int j = 0; j < 4; ++j) { const int e = 4 * j4 + j; const unsigned rw = (e < 8) ? ra[e >> 1] : rb[(e - 8) >> 1]; const float rv = (e & 1) ? bfhi(rw) : bflo(rw);
;                   ov[e] = (xv[e] - mean) * rstd * ng[j] * silu_f(rv); } }
	v_div_scale_f32 v25, s[6:7], v67, v67, v6
	v_rcp_f32_e32 v29, v25
	s_nop 0
	v_fma_f32 v33, -v25, v29, 1.0
	v_fmac_f32_e32 v29, v33, v29
	v_div_scale_f32 v33, vcc, v6, v67, v6
	v_mul_f32_e32 v43, v33, v29
	v_fma_f32 v47, -v25, v43, v33
	v_fmac_f32_e32 v43, v47, v29
	v_fma_f32 v25, -v25, v43, v33
	v_div_fmas_f32 v25, v25, v29, v43
	v_div_fixup_f32 v67, v25, v67, v6
	v_div_scale_f32 v6, s[6:7], v66, v66, v5
	v_rcp_f32_e32 v25, v6
	s_nop 0
	v_fma_f32 v29, -v6, v25, 1.0
	v_fmac_f32_e32 v25, v29, v25
	v_div_scale_f32 v29, vcc, v5, v66, v5
	v_mul_f32_e32 v33, v29, v25
	v_fma_f32 v43, -v6, v33, v29
	v_fmac_f32_e32 v33, v43, v25
	v_fma_f32 v6, -v6, v33, v29
	v_div_fmas_f32 v6, v6, v25, v33
	v_div_fixup_f32 v66, v6, v66, v5
	v_lshlrev_b32_e32 v6, 16, v4
	v_and_b32_e32 v25, 0xffff0000, v4
	v_mul_f32_e32 v4, 0xbfb8aa3b, v6
	v_mul_f32_e32 v5, 0xbfb8aa3b, v25
	v_exp_f32_e32 v4, v4
	v_exp_f32_e32 v5, v5
	s_nop 0
	v_pk_add_f32 v[4:5], v[4:5], 1.0 op_sel_hi:[1,0]
	s_nop 0
	v_div_scale_f32 v29, s[6:7], v5, v5, v25
	v_rcp_f32_e32 v32, v29
	s_nop 0
	v_fma_f32 v33, -v29, v32, 1.0
	v_fmac_f32_e32 v32, v33, v32
	v_div_scale_f32 v33, vcc, v25, v5, v25
	v_mul_f32_e32 v43, v33, v32
	v_fma_f32 v47, -v29, v43, v33
	v_fmac_f32_e32 v43, v47, v32
	v_fma_f32 v29, -v29, v43, v33
	v_div_fmas_f32 v29, v29, v32, v43
	v_div_fixup_f32 v5, v29, v5, v25
	v_div_scale_f32 v25, s[6:7], v4, v4, v6
	v_rcp_f32_e32 v29, v25
	s_nop 0
	v_fma_f32 v32, -v25, v29, 1.0
	v_fmac_f32_e32 v29, v32, v29
	v_div_scale_f32 v32, vcc, v6, v4, v6
	v_mul_f32_e32 v33, v32, v29
	v_fma_f32 v43, -v25, v33, v32
	v_fmac_f32_e32 v33, v43, v29
	v_fma_f32 v25, -v25, v33, v32
	v_div_fmas_f32 v25, v25, v29, v33
	v_lshlrev_b32_e32 v29, 16, v28
	v_and_b32_e32 v28, 0xffff0000, v28
	v_div_fixup_f32 v4, v25, v4, v6
	v_lshlrev_b32_e32 v32, 16, v24
	v_and_b32_e32 v33, 0xffff0000, v24
	v_mul_f32_e32 v24, 0xbfb8aa3b, v29
	v_mul_f32_e32 v25, 0xbfb8aa3b, v28
	v_exp_f32_e32 v24, v24
	v_exp_f32_e32 v25, v25
	v_add_f32_e32 v6, 0, v32
	v_add_f32_e32 v6, v6, v33
	v_add_f32_e32 v6, v6, v68
	v_pk_add_f32 v[24:25], v[24:25], 1.0 op_sel_hi:[1,0]
	v_add_f32_e32 v6, v6, v69
	v_div_scale_f32 v43, s[6:7], v25, v25, v28
	v_rcp_f32_e32 v47, v43
	v_add_f32_e32 v6, v6, v62
	v_add_f32_e32 v6, v6, v63
	v_add_f32_e32 v6, v6, v58
	v_fma_f32 v49, -v43, v47, 1.0
	v_fmac_f32_e32 v47, v49, v47
	v_div_scale_f32 v49, vcc, v28, v25, v28
	v_mul_f32_e32 v76, v49, v47
	v_fma_f32 v77, -v43, v76, v49
	v_fmac_f32_e32 v76, v77, v47
	v_fma_f32 v43, -v43, v76, v49
	v_div_fmas_f32 v43, v43, v47, v76
	v_div_fixup_f32 v25, v43, v25, v28
	v_div_scale_f32 v28, s[6:7], v24, v24, v29
	v_rcp_f32_e32 v43, v28
	v_add_f32_e32 v6, v6, v59
	v_add_f32_e32 v6, v6, v70
	v_add_f32_e32 v6, v6, v71
	v_fma_f32 v47, -v28, v43, 1.0
	v_fmac_f32_e32 v43, v47, v43
	v_div_scale_f32 v47, vcc, v29, v24, v29
	v_add_f32_e32 v6, v6, v64
	v_mul_f32_e32 v49, v47, v43
	v_add_f32_e32 v6, v6, v65
	v_fma_f32 v76, -v28, v49, v47
	v_add_f32_e32 v6, v6, v60
	v_fmac_f32_e32 v49, v76, v43
	v_add_f32_e32 v6, v6, v61
	v_fma_f32 v28, -v28, v49, v47
	v_add_f32_e32 v6, v6, v56
	v_div_fmas_f32 v28, v28, v43, v49
	v_add_f32_e32 v6, v6, v57
	v_div_fixup_f32 v24, v28, v24, v29
	v_mov_b32_e32 v43, v3
	v_mov_b32_e32 v47, v3
	v_mov_b32_e32 v49, v3
	s_nop 1
	v_add_f32_dpp v6, v6, v6 quad_perm:[1,0,3,2] row_mask:0xf bank_mask:0xf
	s_nop 1
	v_add_f32_dpp v6, v6, v6 quad_perm:[2,3,0,1] row_mask:0xf bank_mask:0xf
	s_nop 1
	v_add_f32_dpp v6, v6, v6 row_half_mirror row_mask:0xf bank_mask:0xf
	s_nop 1
	v_add_f32_dpp v6, v6, v6 row_mirror row_mask:0xf bank_mask:0xf
	v_mul_f32_e32 v6, 0x3b800000, v6
	v_pk_add_f32 v[28:29], v[32:33], v[6:7] op_sel_hi:[1,0] neg_lo:[0,1] neg_hi:[0,1]
	v_pk_add_f32 v[68:69], v[68:69], v[6:7] op_sel_hi:[1,0] neg_lo:[0,1] neg_hi:[0,1]
	v_pk_mul_f32 v[32:33], v[28:29], v[28:29]
	v_pk_mul_f32 v[76:77], v[68:69], v[68:69]
	v_pk_add_f32 v[62:63], v[62:63], v[6:7] op_sel_hi:[1,0] neg_lo:[0,1] neg_hi:[0,1]
	v_pk_add_f32 v[58:59], v[58:59], v[6:7] op_sel_hi:[1,0] neg_lo:[0,1] neg_hi:[0,1]
	v_pk_add_f32 v[70:71], v[70:71], v[6:7] op_sel_hi:[1,0] neg_lo:[0,1] neg_hi:[0,1]
	v_pk_add_f32 v[64:65], v[64:65], v[6:7] op_sel_hi:[1,0] neg_lo:[0,1] neg_hi:[0,1]
	v_pk_add_f32 v[60:61], v[60:61], v[6:7] op_sel_hi:[1,0] neg_lo:[0,1] neg_hi:[0,1]
	v_pk_add_f32 v[56:57], v[56:57], v[6:7] op_sel_hi:[1,0] neg_lo:[0,1] neg_hi:[0,1]
	v_add_f32_e32 v6, v32, v33
	v_add_f32_e32 v6, v76, v6
	v_pk_mul_f32 v[78:79], v[62:63], v[62:63]
	v_add_f32_e32 v6, v77, v6
	v_add_f32_e32 v6, v78, v6
	v_pk_mul_f32 v[80:81], v[58:59], v[58:59]
	v_add_f32_e32 v6, v79, v6
	v_add_f32_e32 v6, v80, v6
	v_pk_mul_f32 v[82:83], v[70:71], v[70:71]
	v_add_f32_e32 v6, v81, v6
	v_add_f32_e32 v6, v82, v6
	v_pk_mul_f32 v[84:85], v[64:65], v[64:65]
	v_add_f32_e32 v6, v83, v6
	v_add_f32_e32 v6, v84, v6
	v_pk_mul_f32 v[86:87], v[60:61], v[60:61]
	v_add_f32_e32 v6, v85, v6
	v_add_f32_e32 v6, v86, v6
	v_pk_mul_f32 v[88:89], v[56:57], v[56:57]
	v_add_f32_e32 v6, v87, v6
	v_add_f32_e32 v6, v88, v6
	v_add_f32_e32 v6, v89, v6
	s_nop 1
	v_add_f32_dpp v6, v6, v6 quad_perm:[1,0,3,2] row_mask:0xf bank_mask:0xf
	s_nop 1
	v_add_f32_dpp v6, v6, v6 quad_perm:[2,3,0,1] row_mask:0xf bank_mask:0xf
	s_nop 1
	v_add_f32_dpp v6, v6, v6 row_half_mirror row_mask:0xf bank_mask:0xf
	s_nop 1
	v_add_f32_dpp v6, v6, v6 row_mirror row_mask:0xf bank_mask:0xf
	v_fmamk_f32 v6, v6, 0x3b800000, v213
	v_cmp_gt_f32_e32 vcc, s15, v6
	v_mul_f32_e32 v32, 0x4b800000, v6
	s_nop 0
	v_cndmask_b32_e32 v6, v6, v32, vcc
	v_rsq_f32_e32 v6, v6
	s_nop 0
	v_mul_f32_e32 v32, 0x45800000, v6
	v_cndmask_b32_e32 v6, v6, v32, vcc
	v_pk_mul_f32 v[28:29], v[28:29], v[6:7] op_sel_hi:[1,0]
	s_nop 0
; __device__ __forceinline__ unsigned cvt_pk_bf16(float lo, float hi) { const f32x2v v = {lo, hi}; const b16x2v r = __builtin_convertvector(v, b16x2v); return __builtin_bit_cast(unsigned, r); }
; __device__ __forceinline__ float bflo(unsigned u) { return __uint_as_float(u << 16); }
; __device__ __forceinline__ float bfhi(unsigned u) { return __uint_as_float(u & 0xffff0000u); }
; __device__ __forceinline__ float fexp2(float x) { return __builtin_amdgcn_exp2f(x); }
; __device__ __forceinline__ float silu_f(float v) { return v / (1.0f + fexp2(-v * LOG2E)); }
; __device__ void merge_phase(const Params& p) {
;     ...
;           for (int j4 = 0; j4 < 4; ++j4) { const f32x4 ng = *(const f32x4*)(ngp + 4 * j4);
; #pragma unroll
;               for (int j = 0; j < 4; ++j) { const int e = 4 * j4 + j; const unsigned rw = (e < 8) ? ra[e >> 1] : rb[(e - 8) >> 1]; const float rv = (e & 1) ? bfhi(rw) : bflo(rw);
;                   ov[e] = (xv[e] - mean) * rstd * ng[j] * silu_f(rv); } }
;           u32x4 o0, o1;
; #pragma unroll
;           for (int j = 0; j < 4; ++j) { o0[j] = cvt_pk_bf16(ov[2 * j], ov[2 * j + 1]); o1[j] = cvt_pk_bf16(ov[8 + 2 * j], ov[8 + 2 * j + 1]); }
;           bf16_t* dst = mix + (size_t)tok * DM + hh * 256 + sub * 16;
;           *(u32x4*)dst = o0; *(u32x4*)(dst + 8) = o1; }
;         { const int hd = lane >> 3, sub = lane & 7;
;           const float l0 = lse[(size_t)tok * 8 + hd], l1 = lse[(size_t)T_TOK * 8 + (size_t)tok * 8 + hd], l2 = lse[(size_t)2 * T_TOK * 8 + (size_t)tok * 8 + hd];
;           const float m = fmaxf(l0, fmaxf(l1, l2));
;           float e0 = fexp2((l0 - m) * LOG2E), e1 = fexp2((l1 - m) * LOG2E), e2 = fexp2((l2 - m) * LOG2E);
;           const float inv = 1.0f / (e0 + e1 + e2); e0 *= inv; e1 *= inv; e2 *= inv;
;           const size_t so = (size_t)tok * 1024 + hd * 128 + sub * 16;
;           u32x4 o[2];
; #pragma unroll
;           for (int hf = 0; hf < 2; ++hf) { const u32x4 a = *(const u32x4*)(od0 + so + 8 * hf), b = *(const u32x4*)(od1 + so + 8 * hf), c = *(const u32x4*)(od2 + so + 8 * hf);
; #pragma unroll
;               for (int j = 0; j < 4; ++j) o[hf][j] = cvt_pk_bf16(e0 * bflo(a[j]) + e1 * bflo(b[j]) + e2 * bflo(c[j]), e0 * bfhi(a[j]) + e1 * bfhi(b[j]) + e2 * bfhi(c[j])); }
	v_pk_mul_f32 v[20:21], v[20:21], v[28:29]
	s_nop 0
	v_pk_mul_f32 v[20:21], v[24:25], v[20:21]
	v_pk_mul_f32 v[24:25], v[68:69], v[6:7] op_sel_hi:[1,0]
	s_nop 0
	v_pk_mul_f32 v[22:23], v[22:23], v[24:25]
	v_pk_mul_f32 v[24:25], v[62:63], v[6:7] op_sel_hi:[1,0]
	v_pk_mul_f32 v[22:23], v[66:67], v[22:23]
	v_pk_mul_f32 v[16:17], v[16:17], v[24:25]
	v_pk_mul_f32 v[24:25], v[58:59], v[6:7] op_sel_hi:[1,0]
	v_pk_mul_f32 v[16:17], v[26:27], v[16:17]
	v_pk_mul_f32 v[18:19], v[18:19], v[24:25]
	v_pk_mul_f32 v[24:25], v[70:71], v[6:7] op_sel_hi:[1,0]
	v_pk_mul_f32 v[18:19], v[54:55], v[18:19]
	v_pk_mul_f32 v[12:13], v[12:13], v[24:25]
	s_nop 0
	v_pk_mul_f32 v[12:13], v[4:5], v[12:13]
	v_pk_mul_f32 v[4:5], v[64:65], v[6:7] op_sel_hi:[1,0]
	s_nop 0
	v_pk_mul_f32 v[4:5], v[14:15], v[4:5]
	s_nop 0
	v_pk_mul_f32 v[14:15], v[30:31], v[4:5]
	v_pk_mul_f32 v[4:5], v[60:61], v[6:7] op_sel_hi:[1,0]
	s_nop 0
	v_pk_mul_f32 v[4:5], v[8:9], v[4:5]
	v_lshlrev_b32_e32 v8, 16, v7
	v_and_b32_e32 v9, 0xffff0000, v7
	v_pk_mul_f32 v[24:25], v[34:35], v[4:5]
	v_mul_f32_e32 v4, 0xbfb8aa3b, v8
	v_mul_f32_e32 v5, 0xbfb8aa3b, v9
	v_exp_f32_e32 v4, v4
	v_exp_f32_e32 v5, v5
	v_pk_mul_f32 v[6:7], v[56:57], v[6:7] op_sel_hi:[1,0]
	v_pk_add_f32 v[4:5], v[4:5], 1.0 op_sel_hi:[1,0]
	v_pk_mul_f32 v[6:7], v[10:11], v[6:7]
	v_div_scale_f32 v10, s[6:7], v5, v5, v9
	v_rcp_f32_e32 v11, v10
	s_nop 0
	v_fma_f32 v26, -v10, v11, 1.0
	v_fmac_f32_e32 v11, v26, v11
	v_div_scale_f32 v26, vcc, v9, v5, v9
	v_mul_f32_e32 v27, v26, v11
	v_fma_f32 v28, -v10, v27, v26
	v_fmac_f32_e32 v27, v28, v11
	v_fma_f32 v10, -v10, v27, v26
	v_div_fmas_f32 v10, v10, v11, v27
	v_div_fixup_f32 v5, v10, v5, v9
	v_div_scale_f32 v9, s[6:7], v4, v4, v8
	v_rcp_f32_e32 v10, v9
	s_mov_b32 s6, 0x100000
	v_fma_f32 v11, -v9, v10, 1.0
	v_fmac_f32_e32 v10, v11, v10
	v_div_scale_f32 v11, vcc, v8, v4, v8
	v_mul_f32_e32 v26, v11, v10
	v_fma_f32 v27, -v9, v26, v11
	v_fmac_f32_e32 v26, v27, v10
	v_fma_f32 v9, -v9, v26, v11
	v_div_fmas_f32 v9, v9, v10, v26
	v_div_fixup_f32 v4, v9, v4, v8
	v_cvt_pk_bf16_f32 v8, v12, v13
	v_lshlrev_b64 v[12:13], 13, v[0:1]
	v_sub_co_u32_e32 v12, vcc, 0, v12
	v_pk_mul_f32 v[26:27], v[4:5], v[6:7]
	s_nop 0
	v_subb_co_u32_e32 v13, vcc, 0, v13, vcc
	v_cvt_pk_bf16_f32 v6, v16, v17
	v_lshl_add_u64 v[16:17], v[52:53], 0, v[12:13]
	v_lshl_add_u64 v[12:13], v[16:17], 0, v[2:3]
	v_cvt_pk_bf16_f32 v4, v20, v21
	v_cvt_pk_bf16_f32 v5, v22, v23
	v_cvt_pk_bf16_f32 v7, v18, v19
	v_lshl_add_u64 v[12:13], v[12:13], 0, v[40:41]
	v_cvt_pk_bf16_f32 v9, v14, v15
	v_cvt_pk_bf16_f32 v10, v24, v25
	v_cvt_pk_bf16_f32 v11, v26, v27
	global_store_dwordx4 v[12:13], v[4:7], off
	global_store_dwordx4 v[12:13], v[8:11], off offset:16
	s_nop 0
	v_lshlrev_b64 v[4:5], 5, v[0:1]
	v_lshl_add_u64 v[4:5], s[12:13], 0, v[4:5]
	v_lshl_add_u64 v[4:5], v[4:5], 0, v[42:43]
	v_add_co_u32_e32 v6, vcc, s9, v4
	global_load_dword v1, v[4:5], off nt
	s_nop 0
	v_addc_co_u32_e32 v7, vcc, 0, v5, vcc
	global_load_dword v6, v[6:7], off nt
	v_add_co_u32_e32 v4, vcc, s6, v4
	v_add_u32_e32 v0, s8, v0
	s_nop 0
	v_addc_co_u32_e32 v5, vcc, 0, v5, vcc
	global_load_dword v4, v[4:5], off nt
	s_waitcnt vmcnt(0)
	v_max3_f32 v5, v1, v6, v4
	v_sub_f32_e32 v1, v1, v5
	v_mul_f32_e32 v1, 0x3fb8aa3b, v1
	v_exp_f32_e32 v21, v1
	v_sub_f32_e32 v1, v6, v5
	v_mul_f32_e32 v1, 0x3fb8aa3b, v1
	v_exp_f32_e32 v20, v1
	v_sub_f32_e32 v1, v4, v5
	v_mul_f32_e32 v1, 0x3fb8aa3b, v1
	v_exp_f32_e32 v1, v1
	v_add_f32_e32 v4, v21, v20
	v_add_f32_e32 v4, v1, v4
	v_div_scale_f32 v5, s[6:7], v4, v4, 1.0
	v_rcp_f32_e32 v6, v5
	s_nop 0
	v_fma_f32 v7, -v5, v6, 1.0
	v_fmac_f32_e32 v6, v7, v6
	v_div_scale_f32 v7, vcc, 1.0, v4, 1.0
	v_mul_f32_e32 v8, v7, v6
	v_fma_f32 v9, -v5, v8, v7
	v_fmac_f32_e32 v8, v9, v6
	v_fma_f32 v5, -v5, v8, v7
	v_div_fmas_f32 v5, v5, v6, v8
	v_div_fixup_f32 v22, v5, v4, 1.0
	v_or_b32_e32 v5, v51, v45
	v_or_b32_e32 v4, v50, v44
	v_lshl_add_u64 v[8:9], s[54:55], 0, v[4:5]
	v_lshl_add_u64 v[12:13], s[10:11], 0, v[4:5]
	v_lshl_add_u64 v[32:33], s[24:25], 0, v[4:5]
	global_load_dwordx4 v[4:7], v[8:9], off offset:16 nt
	global_load_dwordx4 v[24:27], v[8:9], off nt
	s_nop 0
	global_load_dwordx4 v[8:11], v[12:13], off offset:16 nt
	global_load_dwordx4 v[28:31], v[12:13], off nt
	s_nop 0
	global_load_dwordx4 v[12:15], v[32:33], off offset:16 nt
	s_nop 0
	global_load_dwordx4 v[32:35], v[32:33], off nt
	v_mul_f32_e32 v18, v1, v22
	v_pk_mul_f32 v[50:51], v[20:21], v[22:23] op_sel_hi:[1,0]
	v_cmp_lt_i32_e32 vcc, s18, v0
	s_or_b64 s[2:3], vcc, s[2:3]
	s_waitcnt vmcnt(4)
; __device__ __forceinline__ unsigned cvt_pk_bf16(float lo, float hi) { const f32x2v v = {lo, hi}; const b16x2v r = __builtin_convertvector(v, b16x2v); return __builtin_bit_cast(unsigned, r); }
; __device__ __forceinline__ float bflo(unsigned u) { return __uint_as_float(u << 16); }
; __device__ __forceinline__ float bfhi(unsigned u) { return __uint_as_float(u & 0xffff0000u); }
; __device__ void merge_phase(const Params& p) {
;     ...
;           for (int hf = 0; hf < 2; ++hf) { const u32x4 a = *(const u32x4*)(od0 + so + 8 * hf), b = *(const u32x4*)(od1 + so + 8 * hf), c = *(const u32x4*)(od2 + so + 8 * hf);
; #pragma unroll
;               for (int j = 0; j < 4; ++j) o[hf][j] = cvt_pk_bf16(e0 * bflo(a[j]) + e1 * bflo(b[j]) + e2 * bflo(c[j]), e0 * bfhi(a[j]) + e1 * bfhi(b[j]) + e2 * bfhi(c[j])); }
;           bf16_t* dst = mix + (size_t)tok * DM + 1024 + hd * 128 + sub * 16;
;           *(u32x4*)dst = o[0]; *(u32x4*)(dst + 8) = o[1]; }
	v_lshlrev_b32_e32 v22, 16, v24
	v_and_b32_e32 v21, 0xffff0000, v24
	s_waitcnt vmcnt(2)
	v_and_b32_e32 v23, 0xffff0000, v28
	v_lshlrev_b32_e32 v20, 16, v28
	v_pk_mul_f32 v[22:23], v[50:51], v[22:23] op_sel:[1,0] op_sel_hi:[0,1]
	v_pk_fma_f32 v[20:21], v[50:51], v[20:21], v[22:23]
	v_and_b32_e32 v23, 0xffff0000, v25
	v_lshlrev_b32_e32 v24, 16, v25
	v_and_b32_e32 v25, 0xffff0000, v29
	v_lshlrev_b32_e32 v22, 16, v29
	v_pk_mul_f32 v[24:25], v[50:51], v[24:25] op_sel:[1,0] op_sel_hi:[0,1]
	s_waitcnt vmcnt(0)
	v_lshlrev_b32_e32 v52, 16, v32
	v_and_b32_e32 v53, 0xffff0000, v32
	v_lshlrev_b32_e32 v28, 16, v33
	v_and_b32_e32 v29, 0xffff0000, v33
	v_pk_fma_f32 v[22:23], v[50:51], v[22:23], v[24:25]
	v_pk_fma_f32 v[20:21], v[18:19], v[52:53], v[20:21] op_sel_hi:[0,1,1]
	v_pk_fma_f32 v[22:23], v[18:19], v[28:29], v[22:23] op_sel_hi:[0,1,1]
	v_lshlrev_b32_e32 v24, 16, v26
	v_and_b32_e32 v25, 0xffff0000, v30
	v_cvt_pk_bf16_f32 v20, v20, v21
	v_cvt_pk_bf16_f32 v21, v22, v23
	v_lshlrev_b32_e32 v22, 16, v30
	v_and_b32_e32 v23, 0xffff0000, v26
	v_pk_mul_f32 v[24:25], v[50:51], v[24:25] op_sel:[1,0] op_sel_hi:[0,1]
	v_pk_fma_f32 v[22:23], v[50:51], v[22:23], v[24:25]
	v_and_b32_e32 v25, 0xffff0000, v27
	v_lshlrev_b32_e32 v26, 16, v27
	v_and_b32_e32 v27, 0xffff0000, v31
	v_lshlrev_b32_e32 v28, 16, v34
	v_and_b32_e32 v29, 0xffff0000, v34
	v_lshlrev_b32_e32 v24, 16, v31
	v_pk_mul_f32 v[26:27], v[50:51], v[26:27] op_sel:[1,0] op_sel_hi:[0,1]
	v_pk_fma_f32 v[22:23], v[18:19], v[28:29], v[22:23] op_sel_hi:[0,1,1]
	v_lshlrev_b32_e32 v28, 16, v35
	v_and_b32_e32 v29, 0xffff0000, v35
	v_pk_fma_f32 v[24:25], v[50:51], v[24:25], v[26:27]
	v_lshlrev_b32_e32 v26, 16, v4
	v_pk_fma_f32 v[24:25], v[18:19], v[28:29], v[24:25] op_sel_hi:[0,1,1]
	v_and_b32_e32 v27, 0xffff0000, v8
	v_cvt_pk_bf16_f32 v22, v22, v23
	v_cvt_pk_bf16_f32 v23, v24, v25
	v_lshlrev_b32_e32 v24, 16, v8
	v_and_b32_e32 v25, 0xffff0000, v4
	v_pk_mul_f32 v[26:27], v[50:51], v[26:27] op_sel:[1,0] op_sel_hi:[0,1]
	v_lshlrev_b32_e32 v28, 16, v12
	v_and_b32_e32 v29, 0xffff0000, v12
	v_pk_fma_f32 v[24:25], v[50:51], v[24:25], v[26:27]
	v_lshlrev_b32_e32 v8, 16, v5
	v_pk_fma_f32 v[24:25], v[18:19], v[28:29], v[24:25] op_sel_hi:[0,1,1]
	v_cvt_pk_bf16_f32 v4, v24, v25
	v_lshlrev_b32_e32 v24, 16, v9
	v_and_b32_e32 v9, 0xffff0000, v9
	v_and_b32_e32 v25, 0xffff0000, v5
	v_pk_mul_f32 v[8:9], v[50:51], v[8:9] op_sel:[1,0] op_sel_hi:[0,1]
	v_lshlrev_b32_e32 v12, 16, v13
	v_and_b32_e32 v13, 0xffff0000, v13
	v_pk_fma_f32 v[8:9], v[50:51], v[24:25], v[8:9]
	v_lshlrev_b32_e32 v24, 16, v14
	v_pk_fma_f32 v[8:9], v[18:19], v[12:13], v[8:9] op_sel_hi:[0,1,1]
	v_lshlrev_b32_e32 v12, 16, v6
	v_and_b32_e32 v13, 0xffff0000, v10
	v_cvt_pk_bf16_f32 v5, v8, v9
	v_lshlrev_b32_e32 v8, 16, v10
	v_and_b32_e32 v9, 0xffff0000, v6
	v_pk_mul_f32 v[12:13], v[50:51], v[12:13] op_sel:[1,0] op_sel_hi:[0,1]
	v_and_b32_e32 v25, 0xffff0000, v14
	v_pk_fma_f32 v[8:9], v[50:51], v[8:9], v[12:13]
	v_lshlrev_b32_e32 v10, 16, v7
	v_pk_fma_f32 v[8:9], v[18:19], v[24:25], v[8:9] op_sel_hi:[0,1,1]
	v_cvt_pk_bf16_f32 v6, v8, v9
	v_lshlrev_b32_e32 v8, 16, v11
	v_and_b32_e32 v11, 0xffff0000, v11
	v_and_b32_e32 v9, 0xffff0000, v7
	v_pk_mul_f32 v[10:11], v[50:51], v[10:11] op_sel:[1,0] op_sel_hi:[0,1]
	v_pk_fma_f32 v[8:9], v[50:51], v[8:9], v[10:11]
	v_lshlrev_b32_e32 v10, 16, v15
	v_and_b32_e32 v11, 0xffff0000, v15
	v_pk_fma_f32 v[8:9], v[18:19], v[10:11], v[8:9] op_sel_hi:[0,1,1]
	v_cvt_pk_bf16_f32 v7, v8, v9
	v_lshl_add_u64 v[8:9], v[16:17], 0, v[46:47]
	v_lshl_add_u64 v[8:9], v[8:9], 0, v[48:49]
	global_store_dwordx4 v[8:9], v[20:23], off offset:2048
	global_store_dwordx4 v[8:9], v[4:7], off offset:2064
	s_andn2_b64 exec, exec, s[2:3]
	s_cbranch_execnz .LBB0_100
